# vAA + s_setprio 1/0 around each MFMA cluster in the attention (P2) loops, 72 clusters
# speedup vs baseline: 1.0036x; 1.0000x over previous
.LBB0_367:
	s_add_i32 s62, s63, 3
	s_add_i32 s38, s61, -16
	s_cmp_lt_i32 s62, 8
	s_cselect_b64 s[0:1], -1, 0
	s_and_b64 s[4:5], s[0:1], exec
	s_cselect_b32 s4, s38, 0x90
	s_add_i32 s4, s4, s57
	s_waitcnt vmcnt(11)
	v_or_b32_e32 v64, s4, v149
	v_med3_i32 v64, v64, 0, v244
	v_add_u32_e32 v65, s4, v194
	v_med3_i32 v65, v65, 0, v244
	v_mul_u32_u24_e32 v176, 0x2800, v64
	s_waitcnt vmcnt(10)
	v_lshl_add_u64 v[68:69], v[164:165], 0, v[176:177]
	v_mul_u32_u24_e32 v176, 0x2800, v65
	s_waitcnt vmcnt(8) lgkmcnt(1)
	v_lshl_add_u64 v[92:93], v[166:167], 0, v[176:177]
	global_load_dwordx4 v[64:67], v[68:69], off offset:1536
	s_nop 0
	global_load_dwordx4 v[68:71], v[68:69], off offset:1600
	s_nop 0
	global_load_dwordx4 v[88:91], v[92:93], off offset:3088
	s_waitcnt lgkmcnt(0)
	global_load_dwordx4 v[92:95], v[92:93], off offset:3072
	s_waitcnt vmcnt(6)
	ds_write_b128 v211, v[76:79]
	ds_write_b128 v211, v[72:75] offset:16
	ds_read_b64_tr_b16 v[72:73], v212
	ds_read_b64_tr_b16 v[74:75], v212 offset:32
	ds_read_b64_tr_b16 v[76:77], v212 offset:64
	ds_read_b64_tr_b16 v[78:79], v212 offset:96
	v_add_u32_e32 v104, s61, v102
	v_add_u32_e32 v105, 0xffffff50, v104
	s_cmp_lg_u32 s63, 6
	s_cselect_b64 s[4:5], -1, 0
	s_cmp_eq_u32 s63, 6
	v_add_u32_e32 v103, s61, v200
	v_cmp_lt_i32_e64 s[48:49], -1, v105
	v_cmp_lt_i32_e64 s[46:47], -2, v105
	v_cmp_lt_i32_e64 s[44:45], -3, v105
	v_cmp_lt_i32_e32 vcc, -4, v105
	s_cbranch_scc1 .LBB0_372
	v_subrev_u32_e32 v101, 48, v103
	v_cmp_gt_u32_e64 s[50:51], s16, v101
	s_waitcnt vmcnt(4)
	s_nop 1
	s_setprio 1
	v_mfma_f32_16x16x32_bf16 v[106:109], v[52:55], v[12:15], 0
	v_mfma_f32_16x16x32_bf16 v[106:109], v[48:51], v[20:23], v[106:109]
	s_nop 7
	s_setprio 0
	v_add_u32_e32 v100, 0xffffff50, v103
	s_and_b64 s[48:49], s[48:49], s[50:51]
	v_cndmask_b32_e64 v106, v245, v106, s[48:49]
	v_cmp_lt_u32_e64 s[48:49], s17, v100
	s_and_b64 s[46:47], s[46:47], s[48:49]
	v_subrev_u32_e32 v100, 46, v103
	v_cndmask_b32_e64 v107, v245, v107, s[46:47]
	v_cmp_gt_u32_e64 s[46:47], s16, v100
	s_and_b64 s[44:45], s[44:45], s[46:47]
	v_subrev_u32_e32 v100, 45, v103
	v_cndmask_b32_e64 v108, v245, v108, s[44:45]
	v_cmp_gt_u32_e64 s[44:45], s16, v100
	s_and_b64 vcc, vcc, s[44:45]
	v_cndmask_b32_e32 v109, v245, v109, vcc
	v_max_f32_e32 v100, v109, v109
	v_max_f32_e32 v101, v108, v108
	v_max_f32_e32 v100, v101, v100
	v_max3_f32 v100, v106, v107, v100
	ds_swizzle_b32 v101, v100 offset:swizzle(SWAP,16)
	s_waitcnt lgkmcnt(0)
	v_max_f32_e32 v101, v101, v101
	v_max_f32_e32 v100, v100, v101
	v_mov_b32_e32 v101, v100
	s_nop 1
	v_permlane32_swap_b32_e32 v100, v101
	v_max_f32_e32 v101, v101, v101
	v_max_f32_e32 v100, v100, v100
	v_max_f32_e32 v100, v100, v101
	v_mul_f32_e32 v100, 0x3e38aa3b, v100
	v_add_f32_e32 v101, 0x41000000, v98
	v_cmp_gt_f32_e32 vcc, v100, v101
	s_cbranch_vccz .LBB0_370
	s_nop 0
	v_cndmask_b32_e32 v100, v98, v100, vcc
	v_sub_f32_e32 v98, v98, v100
	v_exp_f32_e32 v98, v98
	v_mov_b32_e32 v101, v99
	v_mul_f32_e32 v96, v96, v98
	v_pk_mul_f32 v[46:47], v[46:47], v[98:99] op_sel_hi:[1,0]
	v_pk_mul_f32 v[44:45], v[44:45], v[98:99] op_sel_hi:[1,0]
	v_pk_mul_f32 v[38:39], v[38:39], v[98:99] op_sel_hi:[1,0]
	v_pk_mul_f32 v[36:37], v[36:37], v[98:99] op_sel_hi:[1,0]
	v_pk_mul_f32 v[42:43], v[42:43], v[98:99] op_sel_hi:[1,0]
	v_pk_mul_f32 v[40:41], v[40:41], v[98:99] op_sel_hi:[1,0]
	v_pk_mul_f32 v[34:35], v[34:35], v[98:99] op_sel_hi:[1,0]
	v_pk_mul_f32 v[32:33], v[32:33], v[98:99] op_sel_hi:[1,0]
	v_mov_b64_e32 v[98:99], v[100:101]
	s_branch .LBB0_371

.LBB0_371:
	v_fma_f32 v101, v106, s18, -v100
	v_exp_f32_e32 v106, v101
	v_fma_f32 v101, v107, s18, -v100
	v_exp_f32_e32 v110, v101
	v_fma_f32 v101, v108, s18, -v100
	v_fma_f32 v100, v109, s18, -v100
	v_exp_f32_e32 v107, v101
	v_exp_f32_e32 v111, v100
	s_nop 0
	v_pk_add_f32 v[100:101], v[106:107], v[110:111]
	s_nop 0
	v_pk_add_f32 v[100:101], v[100:101], v[100:101] op_sel:[0,1] op_sel_hi:[1,0]
	s_nop 0
	v_pk_add_f32 v[100:101], v[96:97], v[100:101]
	v_cvt_pk_bf16_f32 v96, v106, v110
	s_nop 0
	v_mov_b32_e32 v101, v97
	v_cvt_pk_bf16_f32 v97, v107, v111
	s_nop 0
	s_nop 1
	s_setprio 1
	v_mfma_f32_16x16x16_bf16 v[44:47], v[72:73], v[96:97], v[44:47]
	v_mfma_f32_16x16x16_bf16 v[36:39], v[74:75], v[96:97], v[36:39]
	v_mfma_f32_16x16x16_bf16 v[40:43], v[76:77], v[96:97], v[40:43]
	v_mfma_f32_16x16x16_bf16 v[32:35], v[78:79], v[96:97], v[32:35]
	s_nop 7
	s_setprio 0
	v_mov_b64_e32 v[96:97], v[100:101]
.LBB0_372:
	s_cmp_lt_i32 s62, 1
	s_cbranch_scc1 .LBB0_377
	s_waitcnt vmcnt(4)
	s_nop 1
	s_setprio 1
	v_mfma_f32_16x16x32_bf16 v[106:109], v[52:55], v[24:27], 0
	v_mfma_f32_16x16x32_bf16 v[106:109], v[48:51], v[28:31], v[106:109]
	s_nop 7
	s_setprio 0
	v_subrev_u32_e32 v48, 64, v103
	v_cmp_gt_u32_e32 vcc, s16, v48
	v_cmp_lt_i32_e64 s[44:45], -1, v105
	v_add_u32_e32 v49, 0xffffff40, v103
	s_and_b64 vcc, s[44:45], vcc
	v_cndmask_b32_e32 v48, v245, v106, vcc
	v_cmp_lt_u32_e32 vcc, s17, v49
	v_cmp_lt_i32_e64 s[44:45], -2, v105
	s_and_b64 vcc, s[44:45], vcc
	v_subrev_u32_e32 v50, 62, v103
	v_cndmask_b32_e32 v49, v245, v107, vcc
	v_cmp_gt_u32_e32 vcc, s16, v50
	v_cmp_lt_i32_e64 s[44:45], -3, v105
	s_and_b64 vcc, s[44:45], vcc
	v_subrev_u32_e32 v51, 61, v103
	v_cndmask_b32_e32 v50, v245, v108, vcc
	v_cmp_gt_u32_e32 vcc, s16, v51
	v_cmp_lt_i32_e64 s[44:45], -4, v105
	s_and_b64 vcc, s[44:45], vcc
	v_cndmask_b32_e32 v51, v245, v109, vcc
	v_max_f32_e32 v52, v51, v51
	v_max_f32_e32 v53, v50, v50
	v_max_f32_e32 v52, v53, v52
	v_max3_f32 v52, v48, v49, v52
	ds_swizzle_b32 v53, v52 offset:swizzle(SWAP,16)
	s_waitcnt lgkmcnt(0)
	v_max_f32_e32 v53, v53, v53
	v_max_f32_e32 v52, v52, v53
	v_mov_b32_e32 v53, v52
	s_nop 1
	v_permlane32_swap_b32_e32 v52, v53
	v_max_f32_e32 v53, v53, v53
	v_max_f32_e32 v52, v52, v52
	v_max_f32_e32 v52, v52, v53
	v_mul_f32_e32 v52, 0x3e38aa3b, v52
	v_add_f32_e32 v53, 0x41000000, v99
	v_cmp_gt_f32_e32 vcc, v52, v53
	s_cbranch_vccz .LBB0_375
	s_nop 0
	v_cndmask_b32_e32 v52, v99, v52, vcc
	v_sub_f32_e32 v53, v99, v52
	v_exp_f32_e32 v54, v53
	v_mov_b32_e32 v99, v52
	v_mul_f32_e32 v97, v97, v54
	v_pk_mul_f32 v[18:19], v[18:19], v[54:55] op_sel_hi:[1,0]
	v_pk_mul_f32 v[16:17], v[16:17], v[54:55] op_sel_hi:[1,0]
	v_pk_mul_f32 v[10:11], v[10:11], v[54:55] op_sel_hi:[1,0]
	v_pk_mul_f32 v[8:9], v[8:9], v[54:55] op_sel_hi:[1,0]
	v_pk_mul_f32 v[6:7], v[6:7], v[54:55] op_sel_hi:[1,0]
	v_pk_mul_f32 v[4:5], v[4:5], v[54:55] op_sel_hi:[1,0]
	v_pk_mul_f32 v[2:3], v[2:3], v[54:55] op_sel_hi:[1,0]
	v_pk_mul_f32 v[0:1], v[0:1], v[54:55] op_sel_hi:[1,0]
	s_branch .LBB0_376

.LBB0_376:
	v_fma_f32 v49, v49, s18, -v52
	v_fma_f32 v48, v48, s18, -v52
	v_exp_f32_e32 v54, v49
	v_fma_f32 v49, v50, s18, -v52
	v_fma_f32 v50, v51, s18, -v52
	v_exp_f32_e32 v48, v48
	v_exp_f32_e32 v49, v49
	v_exp_f32_e32 v55, v50
	s_nop 0
	v_pk_add_f32 v[50:51], v[48:49], v[54:55]
	s_nop 0
	v_add_f32_e32 v50, v50, v51
	v_pk_add_f32 v[50:51], v[96:97], v[50:51] op_sel_hi:[1,0]
	v_cvt_pk_bf16_f32 v48, v48, v54
	v_cvt_pk_bf16_f32 v49, v49, v55
	s_nop 0
	v_mov_b32_e32 v97, v51
	s_nop 1
	s_setprio 1
	v_mfma_f32_16x16x16_bf16 v[16:19], v[72:73], v[48:49], v[16:19]
	v_mfma_f32_16x16x16_bf16 v[8:11], v[74:75], v[48:49], v[8:11]
	v_mfma_f32_16x16x16_bf16 v[4:7], v[76:77], v[48:49], v[4:7]
	v_mfma_f32_16x16x16_bf16 v[0:3], v[78:79], v[48:49], v[0:3]
	s_nop 7
	s_setprio 0
.LBB0_377:
	s_cmp_gt_i32 s62, 6
	s_cselect_b64 s[38:39], -1, 0
	s_cmp_lt_i32 s62, 7
	s_cselect_b32 s44, s61, 0x90
	s_add_i32 s44, s44, s57
	s_waitcnt vmcnt(5)
	v_or_b32_e32 v48, s44, v149
	v_med3_i32 v48, v48, 0, v244
	v_add_u32_e32 v49, s44, v194
	v_med3_i32 v50, v49, 0, v244
	v_mul_u32_u24_e32 v176, 0x2800, v48
	v_lshl_add_u64 v[48:49], v[164:165], 0, v[176:177]
	v_mul_u32_u24_e32 v176, 0x2800, v50
	s_waitcnt lgkmcnt(1)
	v_lshl_add_u64 v[76:77], v[166:167], 0, v[176:177]
	global_load_dwordx4 v[52:55], v[48:49], off offset:1536
	s_nop 0
	global_load_dwordx4 v[48:51], v[48:49], off offset:1600
	s_nop 0
	global_load_dwordx4 v[72:75], v[76:77], off offset:3088
	s_waitcnt lgkmcnt(0)
	global_load_dwordx4 v[76:79], v[76:77], off offset:3072
	v_cndmask_b32_e64 v100, 0, 1, s[0:1]
	s_andn2_b64 vcc, exec, s[4:5]
	v_cmp_ne_u32_e64 s[44:45], 1, v100
	s_cbranch_vccnz .LBB0_388
	s_waitcnt vmcnt(8)
	ds_write_b128 v211, v[84:87]
	ds_write_b128 v211, v[80:83] offset:16
	ds_read_b64_tr_b16 v[80:81], v212
	ds_read_b64_tr_b16 v[82:83], v212 offset:32
	ds_read_b64_tr_b16 v[84:85], v212 offset:64
	ds_read_b64_tr_b16 v[86:87], v212 offset:96
	v_add_u32_e32 v105, 0xffffff60, v104
	s_and_b64 vcc, exec, s[44:45]
	v_cmp_lt_i32_e64 s[52:53], -1, v105
	v_cmp_lt_i32_e64 s[50:51], -2, v105
	v_cmp_lt_i32_e64 s[48:49], -3, v105
	v_cmp_lt_i32_e64 s[46:47], -4, v105
	s_cbranch_vccnz .LBB0_383
	v_subrev_u32_e32 v101, 32, v103
	v_cmp_gt_u32_e32 vcc, s16, v101
	s_nop 1
	s_setprio 1
	v_mfma_f32_16x16x32_bf16 v[106:109], v[56:59], v[12:15], 0
	v_mfma_f32_16x16x32_bf16 v[106:109], v[60:63], v[20:23], v[106:109]
	s_nop 7
	s_setprio 0
	v_add_u32_e32 v100, 0xffffff60, v103
	s_and_b64 vcc, s[52:53], vcc
	v_cndmask_b32_e32 v106, v245, v106, vcc
	v_cmp_lt_u32_e32 vcc, s17, v100
	s_and_b64 vcc, s[50:51], vcc
	v_subrev_u32_e32 v100, 30, v103
	v_cndmask_b32_e32 v107, v245, v107, vcc
	v_cmp_gt_u32_e32 vcc, s16, v100
	s_and_b64 vcc, s[48:49], vcc
	v_subrev_u32_e32 v100, 29, v103
	v_cndmask_b32_e32 v108, v245, v108, vcc
	v_cmp_gt_u32_e32 vcc, s16, v100
	s_and_b64 vcc, s[46:47], vcc
	v_max_f32_e32 v101, v108, v108
	v_cndmask_b32_e32 v109, v245, v109, vcc
	v_max_f32_e32 v100, v109, v109
	v_max_f32_e32 v100, v101, v100
	v_max3_f32 v100, v106, v107, v100
	ds_swizzle_b32 v101, v100 offset:swizzle(SWAP,16)
	s_waitcnt lgkmcnt(0)
	v_max_f32_e32 v101, v101, v101
	v_max_f32_e32 v100, v100, v101
	v_mov_b32_e32 v101, v100
	s_nop 1
	v_permlane32_swap_b32_e32 v100, v101
	v_max_f32_e32 v101, v101, v101
	v_max_f32_e32 v100, v100, v100
	v_max_f32_e32 v100, v100, v101
	v_mul_f32_e32 v100, 0x3e38aa3b, v100
	v_add_f32_e32 v101, 0x41000000, v98
	v_cmp_gt_f32_e32 vcc, v100, v101
	s_cbranch_vccz .LBB0_381
	s_nop 0
	v_cndmask_b32_e32 v100, v98, v100, vcc
	v_sub_f32_e32 v98, v98, v100
	v_exp_f32_e32 v98, v98
	v_mov_b32_e32 v101, v99
	v_mul_f32_e32 v96, v96, v98
	v_pk_mul_f32 v[46:47], v[46:47], v[98:99] op_sel_hi:[1,0]
	v_pk_mul_f32 v[44:45], v[44:45], v[98:99] op_sel_hi:[1,0]
	v_pk_mul_f32 v[38:39], v[38:39], v[98:99] op_sel_hi:[1,0]
	v_pk_mul_f32 v[36:37], v[36:37], v[98:99] op_sel_hi:[1,0]
	v_pk_mul_f32 v[42:43], v[42:43], v[98:99] op_sel_hi:[1,0]
	v_pk_mul_f32 v[40:41], v[40:41], v[98:99] op_sel_hi:[1,0]
	v_pk_mul_f32 v[34:35], v[34:35], v[98:99] op_sel_hi:[1,0]
	v_pk_mul_f32 v[32:33], v[32:33], v[98:99] op_sel_hi:[1,0]
	v_mov_b64_e32 v[98:99], v[100:101]
	s_branch .LBB0_382

.LBB0_382:
	v_fma_f32 v101, v106, s18, -v100
	v_exp_f32_e32 v106, v101
	v_fma_f32 v101, v107, s18, -v100
	v_exp_f32_e32 v110, v101
	v_fma_f32 v101, v108, s18, -v100
	v_fma_f32 v100, v109, s18, -v100
	v_exp_f32_e32 v107, v101
	v_exp_f32_e32 v111, v100
	s_nop 0
	v_pk_add_f32 v[100:101], v[106:107], v[110:111]
	s_nop 0
	v_pk_add_f32 v[100:101], v[100:101], v[100:101] op_sel:[0,1] op_sel_hi:[1,0]
	s_nop 0
	v_pk_add_f32 v[100:101], v[96:97], v[100:101]
	v_cvt_pk_bf16_f32 v96, v106, v110
	s_nop 0
	v_mov_b32_e32 v101, v97
	v_cvt_pk_bf16_f32 v97, v107, v111
	s_nop 0
	s_nop 1
	s_setprio 1
	v_mfma_f32_16x16x16_bf16 v[44:47], v[80:81], v[96:97], v[44:47]
	v_mfma_f32_16x16x16_bf16 v[36:39], v[82:83], v[96:97], v[36:39]
	v_mfma_f32_16x16x16_bf16 v[40:43], v[84:85], v[96:97], v[40:43]
	v_mfma_f32_16x16x16_bf16 v[32:35], v[86:87], v[96:97], v[32:35]
	s_nop 7
	s_setprio 0
	v_mov_b64_e32 v[96:97], v[100:101]
.LBB0_383:
	s_cmp_lt_i32 s62, 0
	s_cbranch_scc1 .LBB0_388
	s_nop 1
	s_setprio 1
	v_mfma_f32_16x16x32_bf16 v[106:109], v[56:59], v[24:27], 0
	v_mfma_f32_16x16x32_bf16 v[106:109], v[60:63], v[28:31], v[106:109]
	s_nop 7
	s_setprio 0
	v_subrev_u32_e32 v56, 48, v103
	v_cmp_gt_u32_e32 vcc, s16, v56
	v_cmp_lt_i32_e64 s[46:47], -1, v105
	v_add_u32_e32 v57, 0xffffff50, v103
	s_and_b64 vcc, s[46:47], vcc
	v_cndmask_b32_e32 v56, v245, v106, vcc
	v_cmp_lt_u32_e32 vcc, s17, v57
	v_cmp_lt_i32_e64 s[46:47], -2, v105
	s_and_b64 vcc, s[46:47], vcc
	v_subrev_u32_e32 v58, 46, v103
	v_cndmask_b32_e32 v57, v245, v107, vcc
	v_cmp_gt_u32_e32 vcc, s16, v58
	v_cmp_lt_i32_e64 s[46:47], -3, v105
	s_and_b64 vcc, s[46:47], vcc
	v_subrev_u32_e32 v59, 45, v103
	v_cndmask_b32_e32 v58, v245, v108, vcc
	v_cmp_gt_u32_e32 vcc, s16, v59
	v_cmp_lt_i32_e64 s[46:47], -4, v105
	s_and_b64 vcc, s[46:47], vcc
	v_cndmask_b32_e32 v59, v245, v109, vcc
	v_max_f32_e32 v60, v59, v59
	v_max_f32_e32 v61, v58, v58
	v_max_f32_e32 v60, v61, v60
	v_max3_f32 v60, v56, v57, v60
	ds_swizzle_b32 v61, v60 offset:swizzle(SWAP,16)
	s_waitcnt lgkmcnt(0)
	v_max_f32_e32 v61, v61, v61
	v_max_f32_e32 v60, v60, v61
	v_mov_b32_e32 v61, v60
	s_nop 1
	v_permlane32_swap_b32_e32 v60, v61
	v_max_f32_e32 v61, v61, v61
	v_max_f32_e32 v60, v60, v60
	v_max_f32_e32 v60, v60, v61
	v_mul_f32_e32 v60, 0x3e38aa3b, v60
	v_add_f32_e32 v61, 0x41000000, v99
	v_cmp_gt_f32_e32 vcc, v60, v61
	s_cbranch_vccz .LBB0_386
	s_nop 0
	v_cndmask_b32_e32 v60, v99, v60, vcc
	v_sub_f32_e32 v61, v99, v60
	v_exp_f32_e32 v62, v61
	v_mov_b32_e32 v99, v60
	v_mul_f32_e32 v97, v97, v62
	v_pk_mul_f32 v[18:19], v[18:19], v[62:63] op_sel_hi:[1,0]
	v_pk_mul_f32 v[16:17], v[16:17], v[62:63] op_sel_hi:[1,0]
	v_pk_mul_f32 v[10:11], v[10:11], v[62:63] op_sel_hi:[1,0]
	v_pk_mul_f32 v[8:9], v[8:9], v[62:63] op_sel_hi:[1,0]
	v_pk_mul_f32 v[6:7], v[6:7], v[62:63] op_sel_hi:[1,0]
	v_pk_mul_f32 v[4:5], v[4:5], v[62:63] op_sel_hi:[1,0]
	v_pk_mul_f32 v[2:3], v[2:3], v[62:63] op_sel_hi:[1,0]
	v_pk_mul_f32 v[0:1], v[0:1], v[62:63] op_sel_hi:[1,0]
	s_branch .LBB0_387

.LBB0_387:
	v_fma_f32 v57, v57, s18, -v60
	v_fma_f32 v56, v56, s18, -v60
	v_exp_f32_e32 v62, v57
	v_fma_f32 v57, v58, s18, -v60
	v_fma_f32 v58, v59, s18, -v60
	v_exp_f32_e32 v56, v56
	v_exp_f32_e32 v57, v57
	v_exp_f32_e32 v63, v58
	s_nop 0
	v_pk_add_f32 v[58:59], v[56:57], v[62:63]
	s_nop 0
	v_add_f32_e32 v58, v58, v59
	v_pk_add_f32 v[58:59], v[96:97], v[58:59] op_sel_hi:[1,0]
	v_cvt_pk_bf16_f32 v56, v56, v62
	v_cvt_pk_bf16_f32 v57, v57, v63
	s_nop 0
	v_mov_b32_e32 v97, v59
	s_nop 1
	s_setprio 1
	v_mfma_f32_16x16x16_bf16 v[16:19], v[80:81], v[56:57], v[16:19]
	v_mfma_f32_16x16x16_bf16 v[8:11], v[82:83], v[56:57], v[8:11]
	v_mfma_f32_16x16x16_bf16 v[4:7], v[84:85], v[56:57], v[4:7]
	v_mfma_f32_16x16x16_bf16 v[0:3], v[86:87], v[56:57], v[0:3]
	s_nop 7
	s_setprio 0
.LBB0_388:
	s_min_i32 s0, s62, 5
	s_lshl_b32 s0, s0, 4
	s_add_i32 s0, s60, s0
	v_or_b32_e32 v56, s0, v149
	v_med3_i32 v56, v56, 0, v244
	v_add_u32_e32 v57, s0, v194
	v_med3_i32 v57, v57, 0, v244
	v_mul_u32_u24_e32 v176, 0x2800, v56
	v_lshl_add_u64 v[60:61], v[164:165], 0, v[176:177]
	v_mul_u32_u24_e32 v176, 0x2800, v57
	s_waitcnt vmcnt(8) lgkmcnt(1)
	v_lshl_add_u64 v[84:85], v[166:167], 0, v[176:177]
	global_load_dwordx4 v[56:59], v[60:61], off offset:1536
	s_nop 0
	global_load_dwordx4 v[60:63], v[60:61], off offset:1600
	s_nop 0
	global_load_dwordx4 v[80:83], v[84:85], off offset:3088
	s_waitcnt lgkmcnt(0)
	global_load_dwordx4 v[84:87], v[84:85], off offset:3072
	s_and_b64 vcc, exec, s[44:45]
	s_cbranch_vccnz .LBB0_399
	s_waitcnt vmcnt(8)
	ds_write_b128 v211, v[92:95]
	ds_write_b128 v211, v[88:91] offset:16
	ds_read_b64_tr_b16 v[88:89], v212
	ds_read_b64_tr_b16 v[90:91], v212 offset:32
	ds_read_b64_tr_b16 v[92:93], v212 offset:64
	ds_read_b64_tr_b16 v[94:95], v212 offset:96
	v_add_u32_e32 v104, 0xffffff70, v104
	s_cmp_eq_u32 s63, 4
	v_cmp_lt_i32_e64 s[48:49], -1, v104
	v_cmp_lt_i32_e64 s[46:47], -2, v104
	v_cmp_lt_i32_e64 s[44:45], -3, v104
	v_cmp_lt_i32_e32 vcc, -4, v104
	s_cbranch_scc1 .LBB0_394
	v_add_u32_e32 v101, -16, v103
	v_cmp_gt_u32_e64 s[50:51], s16, v101
	v_add_u32_e32 v100, 0xffffff70, v103
	s_and_b64 s[48:49], s[48:49], s[50:51]
	s_nop 1
	s_setprio 1
	v_mfma_f32_16x16x32_bf16 v[106:109], v[64:67], v[12:15], 0
	v_mfma_f32_16x16x32_bf16 v[106:109], v[68:71], v[20:23], v[106:109]
	s_nop 7
	s_setprio 0
	s_nop 0
	v_cndmask_b32_e64 v105, v245, v106, s[48:49]
	v_cmp_lt_u32_e64 s[48:49], s17, v100
	s_and_b64 s[46:47], s[46:47], s[48:49]
	v_add_u32_e32 v100, -14, v103
	v_cndmask_b32_e64 v106, v245, v107, s[46:47]
	v_cmp_gt_u32_e64 s[46:47], s16, v100
	s_and_b64 s[44:45], s[44:45], s[46:47]
	v_add_u32_e32 v100, -13, v103
	v_cndmask_b32_e64 v107, v245, v108, s[44:45]
	v_cmp_gt_u32_e64 s[44:45], s16, v100
	s_and_b64 vcc, vcc, s[44:45]
	v_cndmask_b32_e32 v108, v245, v109, vcc
	v_max_f32_e32 v100, v108, v108
	v_max_f32_e32 v101, v107, v107
	v_max_f32_e32 v100, v101, v100
	v_max3_f32 v100, v105, v106, v100
	ds_swizzle_b32 v101, v100 offset:swizzle(SWAP,16)
	s_waitcnt lgkmcnt(0)
	v_max_f32_e32 v101, v101, v101
	v_max_f32_e32 v100, v100, v101
	v_mov_b32_e32 v101, v100
	s_nop 1
	v_permlane32_swap_b32_e32 v100, v101
	v_max_f32_e32 v101, v101, v101
	v_max_f32_e32 v100, v100, v100
	v_max_f32_e32 v100, v100, v101
	v_mul_f32_e32 v100, 0x3e38aa3b, v100
	v_add_f32_e32 v101, 0x41000000, v98
	v_cmp_gt_f32_e32 vcc, v100, v101
	s_cbranch_vccz .LBB0_392
	s_nop 0
	v_cndmask_b32_e32 v100, v98, v100, vcc
	v_sub_f32_e32 v98, v98, v100
	v_exp_f32_e32 v98, v98
	v_mov_b32_e32 v101, v99
	v_mul_f32_e32 v96, v96, v98
	v_pk_mul_f32 v[46:47], v[46:47], v[98:99] op_sel_hi:[1,0]
	v_pk_mul_f32 v[44:45], v[44:45], v[98:99] op_sel_hi:[1,0]
	v_pk_mul_f32 v[38:39], v[38:39], v[98:99] op_sel_hi:[1,0]
	v_pk_mul_f32 v[36:37], v[36:37], v[98:99] op_sel_hi:[1,0]
	v_pk_mul_f32 v[42:43], v[42:43], v[98:99] op_sel_hi:[1,0]
	v_pk_mul_f32 v[40:41], v[40:41], v[98:99] op_sel_hi:[1,0]
	v_pk_mul_f32 v[34:35], v[34:35], v[98:99] op_sel_hi:[1,0]
	v_pk_mul_f32 v[32:33], v[32:33], v[98:99] op_sel_hi:[1,0]
	v_mov_b64_e32 v[98:99], v[100:101]
	s_branch .LBB0_393

.LBB0_393:
	v_fma_f32 v101, v105, s18, -v100
	v_exp_f32_e32 v110, v101
	v_fma_f32 v101, v106, s18, -v100
	v_exp_f32_e32 v106, v101
	v_fma_f32 v101, v107, s18, -v100
	v_fma_f32 v100, v108, s18, -v100
	v_exp_f32_e32 v111, v101
	v_exp_f32_e32 v107, v100
	s_nop 0
	v_pk_add_f32 v[100:101], v[110:111], v[106:107]
	s_nop 0
	v_pk_add_f32 v[100:101], v[100:101], v[100:101] op_sel:[0,1] op_sel_hi:[1,0]
	s_nop 0
	v_pk_add_f32 v[100:101], v[96:97], v[100:101]
	v_cvt_pk_bf16_f32 v96, v110, v106
	s_nop 0
	v_mov_b32_e32 v101, v97
	v_cvt_pk_bf16_f32 v97, v111, v107
	s_nop 0
	s_nop 1
	s_setprio 1
	v_mfma_f32_16x16x16_bf16 v[44:47], v[88:89], v[96:97], v[44:47]
	v_mfma_f32_16x16x16_bf16 v[36:39], v[90:91], v[96:97], v[36:39]
	v_mfma_f32_16x16x16_bf16 v[40:43], v[92:93], v[96:97], v[40:43]
	v_mfma_f32_16x16x16_bf16 v[32:35], v[94:95], v[96:97], v[32:35]
	s_nop 7
	s_setprio 0
	v_mov_b64_e32 v[96:97], v[100:101]
.LBB0_394:
	s_cmp_lt_i32 s62, -1
	s_cbranch_scc1 .LBB0_399
	s_nop 1
	s_setprio 1
	v_mfma_f32_16x16x32_bf16 v[106:109], v[64:67], v[24:27], 0
	v_mfma_f32_16x16x32_bf16 v[106:109], v[68:71], v[28:31], v[106:109]
	s_nop 7
	s_setprio 0
	v_subrev_u32_e32 v64, 32, v103
	v_cmp_gt_u32_e32 vcc, s16, v64
	v_cmp_lt_i32_e64 s[44:45], -1, v104
	v_add_u32_e32 v65, 0xffffff60, v103
	s_and_b64 vcc, s[44:45], vcc
	v_cndmask_b32_e32 v64, v245, v106, vcc
	v_cmp_lt_u32_e32 vcc, s17, v65
	v_cmp_lt_i32_e64 s[44:45], -2, v104
	s_and_b64 vcc, s[44:45], vcc
	v_subrev_u32_e32 v66, 30, v103
	v_cndmask_b32_e32 v65, v245, v107, vcc
	v_cmp_gt_u32_e32 vcc, s16, v66
	v_cmp_lt_i32_e64 s[44:45], -3, v104
	s_and_b64 vcc, s[44:45], vcc
	v_subrev_u32_e32 v67, 29, v103
	v_cndmask_b32_e32 v66, v245, v108, vcc
	v_cmp_gt_u32_e32 vcc, s16, v67
	v_cmp_lt_i32_e64 s[44:45], -4, v104
	s_and_b64 vcc, s[44:45], vcc
	v_cndmask_b32_e32 v67, v245, v109, vcc
	v_max_f32_e32 v68, v67, v67
	v_max_f32_e32 v69, v66, v66
	v_max_f32_e32 v68, v69, v68
	v_max3_f32 v68, v64, v65, v68
	ds_swizzle_b32 v69, v68 offset:swizzle(SWAP,16)
	s_waitcnt lgkmcnt(0)
	v_max_f32_e32 v69, v69, v69
	v_max_f32_e32 v68, v68, v69
	v_mov_b32_e32 v69, v68
	s_nop 1
	v_permlane32_swap_b32_e32 v68, v69
	v_max_f32_e32 v69, v69, v69
	v_max_f32_e32 v68, v68, v68
	v_max_f32_e32 v68, v68, v69
	v_mul_f32_e32 v68, 0x3e38aa3b, v68
	v_add_f32_e32 v69, 0x41000000, v99
	v_cmp_gt_f32_e32 vcc, v68, v69
	s_cbranch_vccz .LBB0_397
	s_nop 0
	v_cndmask_b32_e32 v68, v99, v68, vcc
	v_sub_f32_e32 v69, v99, v68
	v_exp_f32_e32 v70, v69
	v_mov_b32_e32 v99, v68
	v_mul_f32_e32 v97, v97, v70
	v_pk_mul_f32 v[18:19], v[18:19], v[70:71] op_sel_hi:[1,0]
	v_pk_mul_f32 v[16:17], v[16:17], v[70:71] op_sel_hi:[1,0]
	v_pk_mul_f32 v[10:11], v[10:11], v[70:71] op_sel_hi:[1,0]
	v_pk_mul_f32 v[8:9], v[8:9], v[70:71] op_sel_hi:[1,0]
	v_pk_mul_f32 v[6:7], v[6:7], v[70:71] op_sel_hi:[1,0]
	v_pk_mul_f32 v[4:5], v[4:5], v[70:71] op_sel_hi:[1,0]
	v_pk_mul_f32 v[2:3], v[2:3], v[70:71] op_sel_hi:[1,0]
	v_pk_mul_f32 v[0:1], v[0:1], v[70:71] op_sel_hi:[1,0]
	s_branch .LBB0_398

.LBB0_398:
	v_fma_f32 v65, v65, s18, -v68
	v_fma_f32 v64, v64, s18, -v68
	v_exp_f32_e32 v70, v65
	v_fma_f32 v65, v66, s18, -v68
	v_fma_f32 v66, v67, s18, -v68
	v_exp_f32_e32 v64, v64
	v_exp_f32_e32 v65, v65
	v_exp_f32_e32 v71, v66
	s_nop 0
	v_pk_add_f32 v[66:67], v[64:65], v[70:71]
	s_nop 0
	v_add_f32_e32 v66, v66, v67
	v_pk_add_f32 v[66:67], v[96:97], v[66:67] op_sel_hi:[1,0]
	v_cvt_pk_bf16_f32 v64, v64, v70
	v_cvt_pk_bf16_f32 v65, v65, v71
	s_nop 0
	v_mov_b32_e32 v97, v67
	s_nop 1
	s_setprio 1
	v_mfma_f32_16x16x16_bf16 v[16:19], v[88:89], v[64:65], v[16:19]
	v_mfma_f32_16x16x16_bf16 v[8:11], v[90:91], v[64:65], v[8:11]
	v_mfma_f32_16x16x16_bf16 v[4:7], v[92:93], v[64:65], v[4:7]
	v_mfma_f32_16x16x16_bf16 v[0:3], v[94:95], v[64:65], v[0:3]
	s_nop 7
	s_setprio 0

.LBB0_407:
	s_cmp_gt_u32 s62, 7
	s_cselect_b64 s[0:1], -1, 0
	s_add_i32 s38, s64, -16
	s_cmp_lt_u32 s62, 8
	s_cselect_b64 s[52:53], -1, 0
	s_and_b64 s[4:5], s[52:53], exec
	s_cselect_b32 s4, s38, 0x90
	s_add_i32 s4, s4, s61
	s_waitcnt vmcnt(11)
	v_or_b32_e32 v48, s4, v149
	v_lshl_add_u32 v48, v48, 2, s8
	v_add_u32_e32 v49, s4, v194
	v_med3_i32 v48, v48, 0, v244
	v_lshl_add_u32 v49, v49, 2, s8
	v_med3_i32 v49, v49, 0, v244
	v_mul_u32_u24_e32 v176, 0x2800, v48
	s_waitcnt vmcnt(10)
	v_lshl_add_u64 v[52:53], v[164:165], 0, v[176:177]
	v_mul_u32_u24_e32 v176, 0x2800, v49
	s_waitcnt vmcnt(8)
	v_lshl_add_u64 v[96:97], v[166:167], 0, v[176:177]
	global_load_dwordx4 v[48:51], v[52:53], off offset:2048
	s_nop 0
	global_load_dwordx4 v[52:55], v[52:53], off offset:2112
	s_nop 0
	global_load_dwordx4 v[92:95], v[96:97], off offset:3600
	s_nop 0
	global_load_dwordx4 v[96:99], v[96:97], off offset:3584
	s_waitcnt vmcnt(6)
	ds_write_b128 v211, v[60:63]
	ds_write_b128 v211, v[56:59] offset:16
	ds_read_b64_tr_b16 v[56:57], v212
	ds_read_b64_tr_b16 v[58:59], v212 offset:32
	ds_read_b64_tr_b16 v[60:61], v212 offset:64
	ds_read_b64_tr_b16 v[62:63], v212 offset:96
	v_add_u32_e32 v172, s64, v155
	v_add_u32_e32 v112, 0xffffff50, v172
	s_cmpk_lg_i32 s64, 0xc0
	s_cselect_b64 s[4:5], -1, 0
	s_cmpk_eq_i32 s64, 0xc0
	v_cmp_lt_i32_e64 s[48:49], -1, v112
	v_cmp_lt_i32_e64 s[46:47], -2, v112
	v_cmp_lt_i32_e64 s[44:45], -3, v112
	v_cmp_lt_i32_e32 vcc, -4, v112
	v_add_u32_e32 v213, s64, v200
	s_cbranch_scc1 .LBB0_412
	v_add_u32_e32 v88, s64, v200
	v_subrev_u32_e32 v90, 48, v88
	v_cmp_gt_u32_e64 s[50:51], s16, v90
	v_add_u32_e32 v89, 0xffffff50, v88
	s_and_b64 s[48:49], s[48:49], s[50:51]
	s_waitcnt vmcnt(4)
	s_nop 1
	s_setprio 1
	v_mfma_f32_16x16x32_bf16 v[100:103], v[44:47], v[16:19], 0
	v_mfma_f32_16x16x32_bf16 v[100:103], v[40:43], v[20:23], v[100:103]
	s_nop 7
	s_setprio 0
	s_nop 0
	v_cndmask_b32_e64 v90, v245, v100, s[48:49]
	v_cmp_lt_u32_e64 s[48:49], s17, v89
	s_and_b64 s[46:47], s[46:47], s[48:49]
	v_subrev_u32_e32 v89, 46, v88
	v_cndmask_b32_e64 v91, v245, v101, s[46:47]
	v_cmp_gt_u32_e64 s[46:47], s16, v89
	s_and_b64 s[44:45], s[44:45], s[46:47]
	v_subrev_u32_e32 v88, 45, v88
	v_cndmask_b32_e64 v100, v245, v102, s[44:45]
	v_cmp_gt_u32_e64 s[44:45], s16, v88
	s_and_b64 vcc, vcc, s[44:45]
	v_cndmask_b32_e32 v101, v245, v103, vcc
	v_max_f32_e32 v88, v101, v101
	v_max_f32_e32 v89, v100, v100
	v_max_f32_e32 v88, v89, v88
	v_max3_f32 v88, v90, v91, v88
	ds_swizzle_b32 v89, v88 offset:swizzle(SWAP,16)
	s_waitcnt lgkmcnt(0)
	v_max_f32_e32 v89, v89, v89
	v_max_f32_e32 v88, v88, v89
	v_mov_b32_e32 v89, v88
	s_nop 1
	v_permlane32_swap_b32_e32 v88, v89
	v_max_f32_e32 v89, v89, v89
	v_max_f32_e32 v88, v88, v88
	v_max_f32_e32 v88, v88, v89
	v_mul_f32_e32 v88, 0x3e38aa3b, v88
	v_add_f32_e32 v89, 0x41000000, v168
	v_cmp_gt_f32_e32 vcc, v88, v89
	s_cbranch_vccz .LBB0_410
	s_nop 0
	v_cndmask_b32_e32 v88, v168, v88, vcc
	v_sub_f32_e32 v89, v168, v88
	v_exp_f32_e32 v102, v89
	v_mov_b32_e32 v89, v169
	v_mov_b64_e32 v[168:169], v[88:89]
	v_mul_f32_e32 v170, v170, v102
	v_pk_mul_f32 v[86:87], v[86:87], v[102:103] op_sel_hi:[1,0]
	v_pk_mul_f32 v[84:85], v[84:85], v[102:103] op_sel_hi:[1,0]
	v_pk_mul_f32 v[82:83], v[82:83], v[102:103] op_sel_hi:[1,0]
	v_pk_mul_f32 v[80:81], v[80:81], v[102:103] op_sel_hi:[1,0]
	v_pk_mul_f32 v[78:79], v[78:79], v[102:103] op_sel_hi:[1,0]
	v_pk_mul_f32 v[76:77], v[76:77], v[102:103] op_sel_hi:[1,0]
	v_pk_mul_f32 v[74:75], v[74:75], v[102:103] op_sel_hi:[1,0]
	v_pk_mul_f32 v[72:73], v[72:73], v[102:103] op_sel_hi:[1,0]
	s_branch .LBB0_411

.LBB0_411:
	v_fma_f32 v89, v90, s18, -v88
	v_exp_f32_e32 v90, v89
	v_fma_f32 v89, v91, s18, -v88
	v_exp_f32_e32 v102, v89
	v_fma_f32 v89, v100, s18, -v88
	v_fma_f32 v88, v101, s18, -v88
	v_exp_f32_e32 v91, v89
	v_exp_f32_e32 v103, v88
	s_nop 0
	v_pk_add_f32 v[88:89], v[90:91], v[102:103]
	s_nop 0
	v_pk_add_f32 v[88:89], v[88:89], v[88:89] op_sel:[0,1] op_sel_hi:[1,0]
	v_cvt_pk_bf16_f32 v90, v90, v102
	v_cvt_pk_bf16_f32 v91, v91, v103
	s_nop 0
	v_pk_add_f32 v[88:89], v[170:171], v[88:89]
	s_nop 1
	s_setprio 1
	v_mfma_f32_16x16x16_bf16 v[84:87], v[56:57], v[90:91], v[84:87]
	v_mfma_f32_16x16x16_bf16 v[80:83], v[58:59], v[90:91], v[80:83]
	v_mfma_f32_16x16x16_bf16 v[76:79], v[60:61], v[90:91], v[76:79]
	v_mfma_f32_16x16x16_bf16 v[72:75], v[62:63], v[90:91], v[72:75]
	s_nop 7
	s_setprio 0
	s_nop 0
	v_mov_b32_e32 v89, v171
	v_mov_b64_e32 v[170:171], v[88:89]
	v_mov_b64_e32 v[102:103], v[74:75]
	v_mov_b64_e32 v[106:107], v[78:79]
	v_mov_b64_e32 v[110:111], v[86:87]
	v_mov_b64_e32 v[90:91], v[82:83]
	v_mov_b64_e32 v[100:101], v[72:73]
	v_mov_b64_e32 v[104:105], v[76:77]
	v_mov_b64_e32 v[108:109], v[84:85]
	v_mov_b64_e32 v[88:89], v[80:81]
.LBB0_412:
	s_cmp_eq_u32 s64, 48
	s_cbranch_scc1 .LBB0_417
	s_waitcnt vmcnt(4)
	s_nop 1
	s_setprio 1
	v_mfma_f32_16x16x32_bf16 v[114:117], v[44:47], v[24:27], 0
	v_mfma_f32_16x16x32_bf16 v[114:117], v[40:43], v[28:31], v[114:117]
	s_nop 7
	s_setprio 0
	v_add_u32_e32 v43, s64, v200
	v_subrev_u32_e32 v40, 64, v43
	v_cmp_gt_u32_e32 vcc, s16, v40
	v_cmp_lt_i32_e64 s[44:45], -1, v112
	v_add_u32_e32 v41, 0xffffff40, v43
	s_and_b64 vcc, s[44:45], vcc
	v_cndmask_b32_e32 v40, v245, v114, vcc
	v_cmp_lt_u32_e32 vcc, s17, v41
	v_cmp_lt_i32_e64 s[44:45], -2, v112
	s_and_b64 vcc, s[44:45], vcc
	v_subrev_u32_e32 v42, 62, v43
	v_cndmask_b32_e32 v41, v245, v115, vcc
	v_cmp_gt_u32_e32 vcc, s16, v42
	v_cmp_lt_i32_e64 s[44:45], -3, v112
	s_and_b64 vcc, s[44:45], vcc
	v_subrev_u32_e32 v43, 61, v43
	v_cndmask_b32_e32 v42, v245, v116, vcc
	v_cmp_gt_u32_e32 vcc, s16, v43
	v_cmp_lt_i32_e64 s[44:45], -4, v112
	s_and_b64 vcc, s[44:45], vcc
	v_cndmask_b32_e32 v43, v245, v117, vcc
	v_max_f32_e32 v44, v43, v43
	v_max_f32_e32 v45, v42, v42
	v_max_f32_e32 v44, v45, v44
	v_max3_f32 v44, v40, v41, v44
	ds_swizzle_b32 v45, v44 offset:swizzle(SWAP,16)
	s_waitcnt lgkmcnt(0)
	v_max_f32_e32 v45, v45, v45
	v_max_f32_e32 v44, v44, v45
	v_mov_b32_e32 v45, v44
	s_nop 1
	v_permlane32_swap_b32_e32 v44, v45
	v_max_f32_e32 v45, v45, v45
	v_max_f32_e32 v44, v44, v44
	v_max_f32_e32 v44, v44, v45
	v_mul_f32_e32 v44, 0x3e38aa3b, v44
	v_add_f32_e32 v45, 0x41000000, v169
	v_cmp_gt_f32_e32 vcc, v44, v45
	s_cbranch_vccz .LBB0_415
	s_nop 0
	v_cndmask_b32_e32 v44, v169, v44, vcc
	v_sub_f32_e32 v45, v169, v44
	v_exp_f32_e32 v46, v45
	v_mov_b32_e32 v169, v44
	v_mul_f32_e32 v171, v171, v46
	v_pk_mul_f32 v[14:15], v[14:15], v[46:47] op_sel_hi:[1,0]
	v_pk_mul_f32 v[12:13], v[12:13], v[46:47] op_sel_hi:[1,0]
	v_pk_mul_f32 v[10:11], v[10:11], v[46:47] op_sel_hi:[1,0]
	v_pk_mul_f32 v[8:9], v[8:9], v[46:47] op_sel_hi:[1,0]
	v_pk_mul_f32 v[6:7], v[6:7], v[46:47] op_sel_hi:[1,0]
	v_pk_mul_f32 v[4:5], v[4:5], v[46:47] op_sel_hi:[1,0]
	v_pk_mul_f32 v[2:3], v[2:3], v[46:47] op_sel_hi:[1,0]
	v_pk_mul_f32 v[0:1], v[0:1], v[46:47] op_sel_hi:[1,0]
	s_branch .LBB0_416

.LBB0_416:
	v_fma_f32 v41, v41, s18, -v44
	v_fma_f32 v40, v40, s18, -v44
	v_exp_f32_e32 v46, v41
	v_fma_f32 v41, v42, s18, -v44
	v_fma_f32 v42, v43, s18, -v44
	v_exp_f32_e32 v40, v40
	v_exp_f32_e32 v41, v41
	v_exp_f32_e32 v47, v42
	s_nop 0
	v_pk_add_f32 v[42:43], v[40:41], v[46:47]
	s_nop 0
	v_add_f32_e32 v42, v42, v43
	v_pk_add_f32 v[42:43], v[170:171], v[42:43] op_sel_hi:[1,0]
	v_cvt_pk_bf16_f32 v40, v40, v46
	v_cvt_pk_bf16_f32 v41, v41, v47
	s_nop 0
	v_mov_b32_e32 v171, v43
	s_nop 1
	s_setprio 1
	v_mfma_f32_16x16x16_bf16 v[12:15], v[56:57], v[40:41], v[12:15]
	v_mfma_f32_16x16x16_bf16 v[8:11], v[58:59], v[40:41], v[8:11]
	v_mfma_f32_16x16x16_bf16 v[4:7], v[60:61], v[40:41], v[4:7]
	v_mfma_f32_16x16x16_bf16 v[0:3], v[62:63], v[40:41], v[0:3]
	s_nop 7
	s_setprio 0

.LBB0_420:
	v_add_u32_e32 v174, 0xffffff60, v172
	s_andn2_b64 vcc, exec, s[0:1]
	v_cmp_lt_i32_e64 s[50:51], -1, v174
	v_cmp_lt_i32_e64 s[48:49], -2, v174
	v_cmp_lt_i32_e64 s[46:47], -3, v174
	v_cmp_lt_i32_e64 s[44:45], -4, v174
	s_cbranch_vccnz .LBB0_424
	v_add_u32_e32 v173, s64, v200
	v_subrev_u32_e32 v89, 32, v173
	v_cmp_gt_u32_e32 vcc, s16, v89
	v_add_u32_e32 v88, 0xffffff60, v173
	s_and_b64 vcc, s[50:51], vcc
	s_nop 1
	s_setprio 1
	v_mfma_f32_16x16x32_bf16 v[100:103], v[32:35], v[16:19], 0
	v_mfma_f32_16x16x32_bf16 v[100:103], v[36:39], v[20:23], v[100:103]
	s_nop 7
	s_setprio 0
	s_nop 0
	v_cndmask_b32_e32 v90, v245, v100, vcc
	v_cmp_lt_u32_e32 vcc, s17, v88
	s_and_b64 vcc, s[48:49], vcc
	v_subrev_u32_e32 v88, 30, v173
	v_cndmask_b32_e32 v91, v245, v101, vcc
	v_cmp_gt_u32_e32 vcc, s16, v88
	s_and_b64 vcc, s[46:47], vcc
	v_subrev_u32_e32 v88, 29, v173
	v_cndmask_b32_e32 v100, v245, v102, vcc
	v_cmp_gt_u32_e32 vcc, s16, v88
	s_and_b64 vcc, s[44:45], vcc
	v_max_f32_e32 v89, v100, v100
	v_cndmask_b32_e32 v101, v245, v103, vcc
	v_max_f32_e32 v88, v101, v101
	v_max_f32_e32 v88, v89, v88
	v_max3_f32 v88, v90, v91, v88
	ds_swizzle_b32 v89, v88 offset:swizzle(SWAP,16)
	s_waitcnt lgkmcnt(0)
	v_max_f32_e32 v89, v89, v89
	v_max_f32_e32 v88, v88, v89
	v_mov_b32_e32 v89, v88
	s_nop 1
	v_permlane32_swap_b32_e32 v88, v89
	v_max_f32_e32 v89, v89, v89
	v_max_f32_e32 v88, v88, v88
	v_max_f32_e32 v88, v88, v89
	v_mul_f32_e32 v88, 0x3e38aa3b, v88
	v_add_f32_e32 v89, 0x41000000, v168
	v_cmp_gt_f32_e32 vcc, v88, v89
	s_cbranch_vccz .LBB0_425
	s_nop 0
	v_cndmask_b32_e32 v88, v168, v88, vcc
	v_sub_f32_e32 v89, v168, v88
	v_exp_f32_e32 v102, v89
	v_mov_b32_e32 v89, v169
	v_mov_b64_e32 v[168:169], v[88:89]
	v_mul_f32_e32 v170, v170, v102
	v_pk_mul_f32 v[86:87], v[86:87], v[102:103] op_sel_hi:[1,0]
	v_pk_mul_f32 v[84:85], v[84:85], v[102:103] op_sel_hi:[1,0]
	v_pk_mul_f32 v[82:83], v[82:83], v[102:103] op_sel_hi:[1,0]
	v_pk_mul_f32 v[80:81], v[80:81], v[102:103] op_sel_hi:[1,0]
	v_pk_mul_f32 v[78:79], v[78:79], v[102:103] op_sel_hi:[1,0]
	v_pk_mul_f32 v[76:77], v[76:77], v[102:103] op_sel_hi:[1,0]
	v_pk_mul_f32 v[74:75], v[74:75], v[102:103] op_sel_hi:[1,0]
	v_pk_mul_f32 v[72:73], v[72:73], v[102:103] op_sel_hi:[1,0]
	s_branch .LBB0_426

.LBB0_426:
	v_fma_f32 v89, v90, s18, -v88
	v_exp_f32_e32 v90, v89
	v_fma_f32 v89, v91, s18, -v88
	v_exp_f32_e32 v102, v89
	v_fma_f32 v89, v100, s18, -v88
	v_fma_f32 v88, v101, s18, -v88
	v_exp_f32_e32 v91, v89
	v_exp_f32_e32 v103, v88
	s_nop 0
	v_pk_add_f32 v[88:89], v[90:91], v[102:103]
	s_nop 0
	v_pk_add_f32 v[88:89], v[88:89], v[88:89] op_sel:[0,1] op_sel_hi:[1,0]
	v_cvt_pk_bf16_f32 v90, v90, v102
	v_cvt_pk_bf16_f32 v91, v91, v103
	s_nop 0
	v_pk_add_f32 v[88:89], v[170:171], v[88:89]
	s_nop 1
	s_setprio 1
	v_mfma_f32_16x16x16_bf16 v[84:87], v[64:65], v[90:91], v[84:87]
	v_mfma_f32_16x16x16_bf16 v[80:83], v[66:67], v[90:91], v[80:83]
	v_mfma_f32_16x16x16_bf16 v[76:79], v[68:69], v[90:91], v[76:79]
	v_mfma_f32_16x16x16_bf16 v[72:75], v[70:71], v[90:91], v[72:75]
	s_nop 7
	s_setprio 0
	s_nop 0
	v_mov_b32_e32 v89, v171
	v_mov_b64_e32 v[114:115], v[86:87]
	v_mov_b64_e32 v[118:119], v[82:83]
	v_mov_b64_e32 v[122:123], v[78:79]
	v_mov_b64_e32 v[126:127], v[74:75]
	v_mov_b64_e32 v[130:131], v[74:75]
	v_mov_b64_e32 v[134:135], v[78:79]
	v_mov_b64_e32 v[138:139], v[86:87]
	v_mov_b64_e32 v[142:143], v[82:83]
	v_mov_b64_e32 v[170:171], v[88:89]
	v_mov_b64_e32 v[112:113], v[84:85]
	v_mov_b64_e32 v[116:117], v[80:81]
	v_mov_b64_e32 v[120:121], v[76:77]
	v_mov_b64_e32 v[124:125], v[72:73]
	v_mov_b64_e32 v[128:129], v[72:73]
	v_mov_b64_e32 v[132:133], v[76:77]
	v_mov_b64_e32 v[136:137], v[84:85]
	v_mov_b64_e32 v[140:141], v[80:81]
.LBB0_427:
	s_nop 1
	s_setprio 1
	v_mfma_f32_16x16x32_bf16 v[72:75], v[32:35], v[24:27], 0
	v_mfma_f32_16x16x32_bf16 v[72:75], v[36:39], v[28:31], v[72:75]
	s_nop 7
	s_setprio 0
	v_subrev_u32_e32 v32, 48, v173
	v_cmp_gt_u32_e32 vcc, s16, v32
	v_cmp_lt_i32_e64 s[44:45], -1, v174
	v_add_u32_e32 v33, 0xffffff50, v173
	s_and_b64 vcc, s[44:45], vcc
	v_cndmask_b32_e32 v32, v245, v72, vcc
	v_cmp_lt_u32_e32 vcc, s17, v33
	v_cmp_lt_i32_e64 s[44:45], -2, v174
	s_and_b64 vcc, s[44:45], vcc
	v_subrev_u32_e32 v34, 46, v173
	v_cndmask_b32_e32 v33, v245, v73, vcc
	v_cmp_gt_u32_e32 vcc, s16, v34
	v_cmp_lt_i32_e64 s[44:45], -3, v174
	s_and_b64 vcc, s[44:45], vcc
	v_subrev_u32_e32 v35, 45, v173
	v_cndmask_b32_e32 v34, v245, v74, vcc
	v_cmp_gt_u32_e32 vcc, s16, v35
	v_cmp_lt_i32_e64 s[44:45], -4, v174
	s_and_b64 vcc, s[44:45], vcc
	v_cndmask_b32_e32 v35, v245, v75, vcc
	v_max_f32_e32 v36, v35, v35
	v_max_f32_e32 v37, v34, v34
	v_max_f32_e32 v36, v37, v36
	v_max3_f32 v36, v32, v33, v36
	ds_swizzle_b32 v37, v36 offset:swizzle(SWAP,16)
	s_waitcnt lgkmcnt(0)
	v_max_f32_e32 v37, v37, v37
	v_max_f32_e32 v36, v36, v37
	v_mov_b32_e32 v37, v36
	s_nop 1
	v_permlane32_swap_b32_e32 v36, v37
	v_max_f32_e32 v37, v37, v37
	v_max_f32_e32 v36, v36, v36
	v_max_f32_e32 v36, v36, v37
	v_mul_f32_e32 v36, 0x3e38aa3b, v36
	v_add_f32_e32 v37, 0x41000000, v169
	v_cmp_gt_f32_e32 vcc, v36, v37
	s_cbranch_vccz .LBB0_429
	s_nop 0
	v_cndmask_b32_e32 v36, v169, v36, vcc
	v_sub_f32_e32 v37, v169, v36
	v_exp_f32_e32 v38, v37
	v_mov_b32_e32 v169, v36
	v_mul_f32_e32 v171, v171, v38
	v_pk_mul_f32 v[14:15], v[14:15], v[38:39] op_sel_hi:[1,0]
	v_pk_mul_f32 v[12:13], v[12:13], v[38:39] op_sel_hi:[1,0]
	v_pk_mul_f32 v[10:11], v[10:11], v[38:39] op_sel_hi:[1,0]
	v_pk_mul_f32 v[8:9], v[8:9], v[38:39] op_sel_hi:[1,0]
	v_pk_mul_f32 v[6:7], v[6:7], v[38:39] op_sel_hi:[1,0]
	v_pk_mul_f32 v[4:5], v[4:5], v[38:39] op_sel_hi:[1,0]
	v_pk_mul_f32 v[2:3], v[2:3], v[38:39] op_sel_hi:[1,0]
	v_pk_mul_f32 v[0:1], v[0:1], v[38:39] op_sel_hi:[1,0]
	s_branch .LBB0_430

.LBB0_430:
	v_fma_f32 v33, v33, s18, -v36
	v_fma_f32 v32, v32, s18, -v36
	v_exp_f32_e32 v38, v33
	v_fma_f32 v33, v34, s18, -v36
	v_fma_f32 v34, v35, s18, -v36
	v_exp_f32_e32 v32, v32
	v_exp_f32_e32 v33, v33
	v_exp_f32_e32 v39, v34
	s_nop 0
	v_pk_add_f32 v[34:35], v[32:33], v[38:39]
	s_nop 0
	v_add_f32_e32 v34, v34, v35
	v_pk_add_f32 v[34:35], v[170:171], v[34:35] op_sel_hi:[1,0]
	v_cvt_pk_bf16_f32 v32, v32, v38
	v_cvt_pk_bf16_f32 v33, v33, v39
	s_nop 0
	v_mov_b32_e32 v171, v35
	s_nop 1
	s_setprio 1
	v_mfma_f32_16x16x16_bf16 v[12:15], v[64:65], v[32:33], v[12:15]
	v_mfma_f32_16x16x16_bf16 v[8:11], v[66:67], v[32:33], v[8:11]
	v_mfma_f32_16x16x16_bf16 v[4:7], v[68:69], v[32:33], v[4:7]
	v_mfma_f32_16x16x16_bf16 v[0:3], v[70:71], v[32:33], v[0:3]
	s_nop 7
	s_setprio 0
.LBB0_431:
	s_min_u32 s0, s62, 5
	s_lshl_b32 s0, s0, 4
	s_add_i32 s0, s63, s0
	v_or_b32_e32 v32, s0, v149
	v_lshl_add_u32 v32, v32, 2, s8
	v_add_u32_e32 v33, s0, v194
	v_med3_i32 v32, v32, 0, v244
	v_lshl_add_u32 v33, v33, 2, s8
	v_med3_i32 v33, v33, 0, v244
	v_mul_u32_u24_e32 v176, 0x2800, v32
	v_lshl_add_u64 v[36:37], v[164:165], 0, v[176:177]
	v_mul_u32_u24_e32 v176, 0x2800, v33
	s_waitcnt vmcnt(8)
	v_lshl_add_u64 v[68:69], v[166:167], 0, v[176:177]
	global_load_dwordx4 v[32:35], v[36:37], off offset:2048
	s_nop 0
	global_load_dwordx4 v[36:39], v[36:37], off offset:2112
	s_nop 0
	global_load_dwordx4 v[64:67], v[68:69], off offset:3600
	s_nop 0
	global_load_dwordx4 v[68:71], v[68:69], off offset:3584
	s_andn2_b64 vcc, exec, s[52:53]
	s_cbranch_vccnz .LBB0_406
	s_waitcnt vmcnt(8)
	ds_write_b128 v211, v[96:99]
	ds_write_b128 v211, v[92:95] offset:16
	ds_read_b64_tr_b16 v[92:93], v212
	ds_read_b64_tr_b16 v[94:95], v212 offset:32
	ds_read_b64_tr_b16 v[96:97], v212 offset:64
	ds_read_b64_tr_b16 v[98:99], v212 offset:96
	v_add_u32_e32 v176, 0xffffff70, v172
	s_mov_b64 s[0:1], -1
	s_cmpk_lg_i32 s64, 0xa0
	v_cmp_lt_i32_e64 s[48:49], -1, v176
	v_cmp_lt_i32_e64 s[46:47], -2, v176
	v_cmp_lt_i32_e64 s[44:45], -3, v176
	v_cmp_lt_i32_e32 vcc, -4, v176
	s_cbranch_scc0 .LBB0_436
	v_add_u32_e32 v214, s64, v200
	v_add_u32_e32 v73, -16, v214
	v_cmp_gt_u32_e64 s[50:51], s16, v73
	s_nop 1
	s_setprio 1
	v_mfma_f32_16x16x32_bf16 v[74:77], v[48:51], v[16:19], 0
	v_mfma_f32_16x16x32_bf16 v[74:77], v[52:55], v[20:23], v[74:77]
	s_nop 7
	s_setprio 0
	v_add_u32_e32 v72, 0xffffff70, v214
	s_and_b64 s[48:49], s[48:49], s[50:51]
	v_cndmask_b32_e64 v74, v245, v74, s[48:49]
	v_cmp_lt_u32_e64 s[48:49], s17, v72
	s_and_b64 s[46:47], s[46:47], s[48:49]
	v_add_u32_e32 v72, -14, v214
	v_cndmask_b32_e64 v75, v245, v75, s[46:47]
	v_cmp_gt_u32_e64 s[46:47], s16, v72
	s_and_b64 s[44:45], s[44:45], s[46:47]
	v_add_u32_e32 v72, -13, v214
	v_cndmask_b32_e64 v76, v245, v76, s[44:45]
	v_cmp_gt_u32_e64 s[44:45], s16, v72
	s_and_b64 vcc, vcc, s[44:45]
	v_cndmask_b32_e32 v77, v245, v77, vcc
	v_max_f32_e32 v72, v77, v77
	v_max_f32_e32 v73, v76, v76
	v_max_f32_e32 v72, v73, v72
	v_max3_f32 v72, v74, v75, v72
	ds_swizzle_b32 v73, v72 offset:swizzle(SWAP,16)
	v_mov_b64_e32 v[100:101], v[124:125]
	v_mov_b64_e32 v[104:105], v[120:121]
	v_mov_b64_e32 v[88:89], v[116:117]
	v_mov_b64_e32 v[108:109], v[112:113]
	s_waitcnt lgkmcnt(0)
	v_max_f32_e32 v73, v73, v73
	v_max_f32_e32 v72, v72, v73
	v_mov_b32_e32 v73, v72
	s_nop 1
	v_permlane32_swap_b32_e32 v72, v73
	v_max_f32_e32 v73, v73, v73
	v_max_f32_e32 v72, v72, v72
	v_max_f32_e32 v72, v72, v73
	v_mul_f32_e32 v79, 0x3e38aa3b, v72
	v_add_f32_e32 v72, 0x41000000, v168
	v_cmp_gt_f32_e32 vcc, v79, v72
	v_mov_b64_e32 v[102:103], v[126:127]
	v_mov_b64_e32 v[106:107], v[122:123]
	v_mov_b64_e32 v[90:91], v[118:119]
	v_mov_b64_e32 v[110:111], v[114:115]
	v_mov_b64_e32 v[72:73], v[170:171]
	v_mov_b64_e32 v[172:173], v[168:169]
	v_mov_b32_e32 v78, v168
	s_cbranch_vccz .LBB0_435
	v_cndmask_b32_e32 v172, v168, v79, vcc
	v_sub_f32_e32 v72, v168, v172
	v_exp_f32_e32 v78, v72
	v_mov_b32_e32 v173, v169
	v_mov_b32_e32 v73, v171
	v_mul_f32_e32 v72, v170, v78
	v_pk_mul_f32 v[110:111], v[114:115], v[78:79] op_sel_hi:[1,0]
	v_pk_mul_f32 v[108:109], v[112:113], v[78:79] op_sel_hi:[1,0]
	v_pk_mul_f32 v[90:91], v[118:119], v[78:79] op_sel_hi:[1,0]
	v_pk_mul_f32 v[88:89], v[116:117], v[78:79] op_sel_hi:[1,0]
	v_pk_mul_f32 v[106:107], v[122:123], v[78:79] op_sel_hi:[1,0]
	v_pk_mul_f32 v[104:105], v[120:121], v[78:79] op_sel_hi:[1,0]
	v_pk_mul_f32 v[102:103], v[126:127], v[78:79] op_sel_hi:[1,0]
	v_pk_mul_f32 v[100:101], v[124:125], v[78:79] op_sel_hi:[1,0]
	v_mov_b32_e32 v78, v172
.LBB0_435:
	v_fma_f32 v75, v75, s18, -v78
	v_fma_f32 v74, v74, s18, -v78
	v_exp_f32_e32 v80, v75
	v_fma_f32 v75, v76, s18, -v78
	v_fma_f32 v76, v77, s18, -v78
	v_exp_f32_e32 v74, v74
	v_exp_f32_e32 v75, v75
	v_exp_f32_e32 v81, v76
	s_mov_b64 s[0:1], 0
	v_pk_add_f32 v[76:77], v[74:75], v[80:81]
	s_nop 0
	v_pk_add_f32 v[76:77], v[76:77], v[76:77] op_sel:[0,1] op_sel_hi:[1,0]
	s_nop 0
	v_pk_add_f32 v[174:175], v[72:73], v[76:77]
	v_cvt_pk_bf16_f32 v72, v74, v80
	s_nop 0
	v_mov_b32_e32 v175, v73
	v_cvt_pk_bf16_f32 v73, v75, v81
	s_nop 0
	s_nop 1
	s_setprio 1
	v_mfma_f32_16x16x16_bf16 v[108:111], v[92:93], v[72:73], v[108:111]
	v_mfma_f32_16x16x16_bf16 v[88:91], v[94:95], v[72:73], v[88:91]
	v_mfma_f32_16x16x16_bf16 v[104:107], v[96:97], v[72:73], v[104:107]
	v_mfma_f32_16x16x16_bf16 v[100:103], v[98:99], v[72:73], v[100:103]
	s_nop 7
	s_setprio 0

.LBB0_438:
	s_nop 1
	s_setprio 1
	v_mfma_f32_16x16x32_bf16 v[112:115], v[48:51], v[24:27], 0
	v_mfma_f32_16x16x32_bf16 v[112:115], v[52:55], v[28:31], v[112:115]
	s_nop 7
	s_setprio 0
	v_subrev_u32_e32 v48, 32, v214
	v_cmp_gt_u32_e32 vcc, s16, v48
	v_cmp_lt_i32_e64 s[44:45], -1, v176
	v_add_u32_e32 v49, 0xffffff60, v214
	s_and_b64 vcc, s[44:45], vcc
	v_cndmask_b32_e32 v48, v245, v112, vcc
	v_cmp_lt_u32_e32 vcc, s17, v49
	v_cmp_lt_i32_e64 s[44:45], -2, v176
	s_and_b64 vcc, s[44:45], vcc
	v_subrev_u32_e32 v50, 30, v214
	v_cndmask_b32_e32 v49, v245, v113, vcc
	v_cmp_gt_u32_e32 vcc, s16, v50
	v_cmp_lt_i32_e64 s[44:45], -3, v176
	s_and_b64 vcc, s[44:45], vcc
	v_subrev_u32_e32 v51, 29, v214
	v_cndmask_b32_e32 v50, v245, v114, vcc
	v_cmp_gt_u32_e32 vcc, s16, v51
	v_cmp_lt_i32_e64 s[44:45], -4, v176
	s_and_b64 vcc, s[44:45], vcc
	v_cndmask_b32_e32 v51, v245, v115, vcc
	v_max_f32_e32 v52, v51, v51
	v_max_f32_e32 v53, v50, v50
	v_max_f32_e32 v52, v53, v52
	v_max3_f32 v52, v48, v49, v52
	ds_swizzle_b32 v53, v52 offset:swizzle(SWAP,16)
	s_waitcnt lgkmcnt(0)
	v_max_f32_e32 v53, v53, v53
	v_max_f32_e32 v52, v52, v53
	v_mov_b32_e32 v53, v52
	s_nop 1
	v_permlane32_swap_b32_e32 v52, v53
	v_max_f32_e32 v53, v53, v53
	v_max_f32_e32 v52, v52, v52
	v_max_f32_e32 v52, v52, v53
	v_mul_f32_e32 v52, 0x3e38aa3b, v52
	v_add_f32_e32 v53, 0x41000000, v173
	v_cmp_gt_f32_e32 vcc, v52, v53
	s_cbranch_vccz .LBB0_440
	s_nop 0
	v_cndmask_b32_e32 v52, v173, v52, vcc
	v_sub_f32_e32 v53, v173, v52
	v_exp_f32_e32 v54, v53
	v_mov_b32_e32 v173, v52
	v_mul_f32_e32 v175, v175, v54
	v_pk_mul_f32 v[14:15], v[14:15], v[54:55] op_sel_hi:[1,0]
	v_pk_mul_f32 v[12:13], v[12:13], v[54:55] op_sel_hi:[1,0]
	v_pk_mul_f32 v[10:11], v[10:11], v[54:55] op_sel_hi:[1,0]
	v_pk_mul_f32 v[8:9], v[8:9], v[54:55] op_sel_hi:[1,0]
	v_pk_mul_f32 v[6:7], v[6:7], v[54:55] op_sel_hi:[1,0]
	v_pk_mul_f32 v[4:5], v[4:5], v[54:55] op_sel_hi:[1,0]
	v_pk_mul_f32 v[2:3], v[2:3], v[54:55] op_sel_hi:[1,0]
	v_pk_mul_f32 v[0:1], v[0:1], v[54:55] op_sel_hi:[1,0]
	s_branch .LBB0_441

.LBB0_441:
	v_fma_f32 v49, v49, s18, -v52
	v_fma_f32 v48, v48, s18, -v52
	v_exp_f32_e32 v54, v49
	v_fma_f32 v49, v50, s18, -v52
	v_fma_f32 v50, v51, s18, -v52
	v_exp_f32_e32 v48, v48
	v_exp_f32_e32 v49, v49
	v_exp_f32_e32 v55, v50
	v_mov_b64_e32 v[168:169], v[172:173]
	v_pk_add_f32 v[50:51], v[48:49], v[54:55]
	s_nop 0
	v_add_f32_e32 v50, v50, v51
	v_pk_add_f32 v[50:51], v[174:175], v[50:51] op_sel_hi:[1,0]
	v_cvt_pk_bf16_f32 v48, v48, v54
	v_cvt_pk_bf16_f32 v49, v49, v55
	s_nop 0
	v_mov_b32_e32 v175, v51
	v_mov_b64_e32 v[170:171], v[174:175]
	s_nop 1
	s_setprio 1
	v_mfma_f32_16x16x16_bf16 v[12:15], v[92:93], v[48:49], v[12:15]
	v_mfma_f32_16x16x16_bf16 v[8:11], v[94:95], v[48:49], v[8:11]
	v_mfma_f32_16x16x16_bf16 v[4:7], v[96:97], v[48:49], v[4:7]
	v_mfma_f32_16x16x16_bf16 v[0:3], v[98:99], v[48:49], v[0:3]
	s_nop 7
	s_setprio 0
	s_add_i32 s62, s62, 3
	s_add_i32 s64, s64, 48
	s_and_b64 vcc, exec, s[38:39]
	s_cbranch_vccz .LBB0_407

.LBB0_447:
	v_fmamk_f32 v53, v53, 0x3e38aa3b, v86
	v_fmamk_f32 v52, v52, 0x3e38aa3b, v86
	v_exp_f32_e32 v56, v53
	v_fmamk_f32 v53, v54, 0x3e38aa3b, v86
	v_fmac_f32_e32 v86, 0x3e38aa3b, v55
	v_exp_f32_e32 v52, v52
	v_exp_f32_e32 v53, v53
	v_exp_f32_e32 v57, v86
	s_add_i32 s46, s46, 3
	s_andn2_b64 vcc, exec, s[0:1]
	s_add_i32 s39, s39, 48
	v_pk_add_f32 v[54:55], v[52:53], v[56:57]
	v_cvt_pk_bf16_f32 v52, v52, v56
	v_cvt_pk_bf16_f32 v53, v53, v57
	s_nop 0
	v_add_f32_e32 v54, v54, v55
	v_add_f32_e32 v86, v87, v54
	s_nop 1
	s_setprio 1
	v_mfma_f32_16x16x16_bf16 v[48:51], v[60:61], v[52:53], v[48:51]
	v_mfma_f32_16x16x16_bf16 v[12:15], v[62:63], v[52:53], v[12:15]
	v_mfma_f32_16x16x16_bf16 v[68:71], v[64:65], v[52:53], v[68:71]
	v_mfma_f32_16x16x16_bf16 v[8:11], v[66:67], v[52:53], v[8:11]
	s_nop 7
	s_setprio 0
	s_cbranch_vccz .LBB0_455
.LBB0_448:
	s_add_i32 s47, s4, s39
	s_add_i32 s0, s47, 0xa0
	s_cmp_lt_u32 s46, 7
	s_cselect_b32 s0, s0, 0x80
	s_add_i32 s0, s0, s5
	v_or_b32_e32 v52, s0, v149
	v_lshl_add_u32 v52, v52, 4, s9
	v_add_u32_e32 v53, s0, v194
	v_med3_i32 v52, v52, 0, v244
	v_lshl_add_u32 v53, v53, 4, s9
	v_med3_i32 v53, v53, 0, v244
	v_mul_u32_u24_e32 v176, 0x2800, v52
	v_lshl_add_u64 v[56:57], v[72:73], 0, v[176:177]
	v_mul_u32_u24_e32 v176, 0x2800, v53
	v_lshl_add_u64 v[64:65], v[74:75], 0, v[176:177]
	global_load_dwordx4 v[52:55], v[56:57], off offset:2560
	s_nop 0
	global_load_dwordx4 v[56:59], v[56:57], off offset:2624
	s_nop 0
	global_load_dwordx4 v[60:63], v[64:65], off offset:16
	s_nop 0
	global_load_dwordx4 v[64:67], v[64:65], off
	s_waitcnt vmcnt(6)
	ds_write_b128 v211, v[28:31]
	ds_write_b128 v211, v[16:19] offset:16
	v_add_u32_e32 v83, s39, v78
	ds_read_b64_tr_b16 v[16:17], v212
	ds_read_b64_tr_b16 v[18:19], v212 offset:32
	ds_read_b64_tr_b16 v[28:29], v212 offset:64
	ds_read_b64_tr_b16 v[30:31], v212 offset:96
	v_add_u32_e32 v84, s39, v195
	s_waitcnt vmcnt(4)
	s_nop 1
	s_setprio 1
	v_mfma_f32_16x16x32_bf16 v[88:91], v[20:23], v[0:3], 0
	v_mfma_f32_16x16x32_bf16 v[88:91], v[24:27], v[4:7], v[88:91]
	s_nop 7
	s_setprio 0
	v_add_u32_e32 v20, 0x80, v83
	v_cmp_gt_u32_e32 vcc, s16, v20
	v_cmp_lt_i32_e64 s[44:45], -1, v84
	s_and_b64 vcc, s[44:45], vcc
	v_cndmask_b32_e32 v20, v245, v88, vcc
	v_cmp_lt_u32_e32 vcc, s17, v83
	v_cmp_lt_i32_e64 s[44:45], -2, v84
	s_and_b64 vcc, s[44:45], vcc
	v_add_u32_e32 v22, 0x82, v83
	v_cndmask_b32_e32 v21, v245, v89, vcc
	v_cmp_gt_u32_e32 vcc, s16, v22
	v_cmp_lt_i32_e64 s[44:45], -3, v84
	s_and_b64 vcc, s[44:45], vcc
	v_add_u32_e32 v23, 0x83, v83
	v_cndmask_b32_e32 v22, v245, v90, vcc
	v_cmp_gt_u32_e32 vcc, s16, v23
	v_cmp_lt_i32_e64 s[44:45], -4, v84
	s_and_b64 vcc, s[44:45], vcc
	v_cndmask_b32_e32 v23, v245, v91, vcc
	v_max_f32_e32 v24, v23, v23
	v_max_f32_e32 v25, v22, v22
	v_max_f32_e32 v24, v25, v24
	v_max3_f32 v24, v20, v21, v24
	ds_swizzle_b32 v25, v24 offset:swizzle(SWAP,16)
	v_add_f32_e32 v85, 0x41000000, v82
	s_waitcnt lgkmcnt(0)
	v_max_f32_e32 v25, v25, v25
	v_max_f32_e32 v24, v24, v25
	v_mov_b32_e32 v25, v24
	s_nop 1
	v_permlane32_swap_b32_e32 v24, v25
	v_max_f32_e32 v25, v25, v25
	v_max_f32_e32 v24, v24, v24
	v_max_f32_e32 v24, v24, v25
	v_mul_f32_e32 v24, 0x3e38aa3b, v24
	v_cmp_gt_f32_e32 vcc, v24, v85
	s_cbranch_vccz .LBB0_450
	s_nop 0
	v_cndmask_b32_e32 v25, v82, v24, vcc
	v_sub_f32_e32 v24, v82, v25
	v_exp_f32_e32 v24, v24
	v_add_f32_e32 v85, 0x41000000, v25
	v_mov_b32_e32 v82, v25
	v_mul_f32_e32 v86, v86, v24
	v_pk_mul_f32 v[10:11], v[10:11], v[24:25] op_sel_hi:[1,0]
	v_pk_mul_f32 v[8:9], v[8:9], v[24:25] op_sel_hi:[1,0]
	v_pk_mul_f32 v[70:71], v[70:71], v[24:25] op_sel_hi:[1,0]
	v_pk_mul_f32 v[68:69], v[68:69], v[24:25] op_sel_hi:[1,0]
	v_pk_mul_f32 v[14:15], v[14:15], v[24:25] op_sel_hi:[1,0]
	v_pk_mul_f32 v[12:13], v[12:13], v[24:25] op_sel_hi:[1,0]
	v_pk_mul_f32 v[50:51], v[50:51], v[24:25] op_sel_hi:[1,0]
	v_pk_mul_f32 v[48:49], v[48:49], v[24:25] op_sel_hi:[1,0]
.LBB0_450:
	v_fma_f32 v21, v21, s18, -v82
	v_fma_f32 v20, v20, s18, -v82
	v_exp_f32_e32 v24, v21
	v_fma_f32 v21, v22, s18, -v82
	v_fma_f32 v22, v23, s18, -v82
	s_cmp_gt_u32 s46, 5
	v_exp_f32_e32 v20, v20
	v_exp_f32_e32 v21, v21
	v_exp_f32_e32 v25, v22
	s_cselect_b64 s[0:1], -1, 0
	s_addk_i32 s47, 0xb0
	s_cmp_lt_u32 s46, 6
	s_cselect_b32 s44, s47, 0x80
	s_add_i32 s44, s44, s5
	v_pk_add_f32 v[22:23], v[20:21], v[24:25]
	v_cvt_pk_bf16_f32 v20, v20, v24
	v_cvt_pk_bf16_f32 v21, v21, v25
	s_nop 0
	s_nop 1
	s_setprio 1
	v_mfma_f32_16x16x16_bf16 v[48:51], v[16:17], v[20:21], v[48:51]
	v_mfma_f32_16x16x16_bf16 v[12:15], v[18:19], v[20:21], v[12:15]
	v_mfma_f32_16x16x16_bf16 v[68:71], v[28:29], v[20:21], v[68:71]
	v_mfma_f32_16x16x16_bf16 v[8:11], v[30:31], v[20:21], v[8:11]
	s_nop 7
	s_setprio 0
	v_or_b32_e32 v16, s44, v149
	v_lshl_add_u32 v16, v16, 4, s9
	v_add_u32_e32 v17, s44, v194
	v_med3_i32 v16, v16, 0, v244
	v_lshl_add_u32 v17, v17, 4, s9
	v_med3_i32 v18, v17, 0, v244
	v_mul_u32_u24_e32 v176, 0x2800, v16
	v_lshl_add_u64 v[16:17], v[72:73], 0, v[176:177]
	v_mul_u32_u24_e32 v176, 0x2800, v18
	v_add_f32_e32 v22, v22, v23
	v_lshl_add_u64 v[28:29], v[74:75], 0, v[176:177]
	v_add_f32_e32 v87, v86, v22
	global_load_dwordx4 v[20:23], v[16:17], off offset:2560
	global_load_dwordx4 v[24:27], v[16:17], off offset:2624
	s_nop 0
	global_load_dwordx4 v[16:19], v[28:29], off offset:16
	s_nop 0
	global_load_dwordx4 v[28:31], v[28:29], off
	ds_write_b128 v211, v[36:39]
	ds_write_b128 v211, v[32:35] offset:16
	ds_read_b64_tr_b16 v[32:33], v212
	ds_read_b64_tr_b16 v[34:35], v212 offset:32
	ds_read_b64_tr_b16 v[36:37], v212 offset:64
	ds_read_b64_tr_b16 v[38:39], v212 offset:96
	v_add_u32_e32 v86, 16, v84
	s_nop 1
	s_setprio 1
	v_mfma_f32_16x16x32_bf16 v[88:91], v[40:43], v[0:3], 0
	v_mfma_f32_16x16x32_bf16 v[88:91], v[44:47], v[4:7], v[88:91]
	s_nop 7
	s_setprio 0
	v_add_u32_e32 v40, 0x90, v83
	v_cmp_gt_u32_e32 vcc, s16, v40
	v_cmp_lt_i32_e64 s[44:45], -1, v86
	v_add_u32_e32 v41, 16, v83
	s_and_b64 vcc, s[44:45], vcc
	v_cndmask_b32_e32 v40, v245, v88, vcc
	v_cmp_lt_u32_e32 vcc, s17, v41
	v_cmp_lt_i32_e64 s[44:45], -2, v86
	s_and_b64 vcc, s[44:45], vcc
	v_add_u32_e32 v42, 0x92, v83
	v_cndmask_b32_e32 v41, v245, v89, vcc
	v_cmp_gt_u32_e32 vcc, s16, v42
	v_cmp_lt_i32_e64 s[44:45], -3, v86
	s_and_b64 vcc, s[44:45], vcc
	v_add_u32_e32 v43, 0x93, v83
	v_cndmask_b32_e32 v42, v245, v90, vcc
	v_cmp_gt_u32_e32 vcc, s16, v43
	v_cmp_lt_i32_e64 s[44:45], -4, v86
	s_and_b64 vcc, s[44:45], vcc
	v_cndmask_b32_e32 v43, v245, v91, vcc
	v_max_f32_e32 v44, v43, v43
	v_max_f32_e32 v45, v42, v42
	v_max_f32_e32 v44, v45, v44
	v_max3_f32 v44, v40, v41, v44
	ds_swizzle_b32 v45, v44 offset:swizzle(SWAP,16)
	s_waitcnt lgkmcnt(0)
	v_max_f32_e32 v45, v45, v45
	v_max_f32_e32 v44, v44, v45
	v_mov_b32_e32 v45, v44
	s_nop 1
	v_permlane32_swap_b32_e32 v44, v45
	v_max_f32_e32 v45, v45, v45
	v_max_f32_e32 v44, v44, v44
	v_max_f32_e32 v44, v44, v45
	v_mul_f32_e32 v44, 0x3e38aa3b, v44
	v_cmp_gt_f32_e32 vcc, v44, v85
	s_cbranch_vccz .LBB0_452
	s_nop 0
	v_cndmask_b32_e32 v45, v82, v44, vcc
	v_sub_f32_e32 v44, v82, v45
	v_exp_f32_e32 v44, v44
	v_xor_b32_e32 v86, 0x80000000, v45
	v_add_f32_e32 v85, 0x41000000, v45
	v_mov_b32_e32 v82, v45
	v_mul_f32_e32 v87, v87, v44
	v_pk_mul_f32 v[50:51], v[50:51], v[44:45] op_sel_hi:[1,0]
	v_pk_mul_f32 v[48:49], v[48:49], v[44:45] op_sel_hi:[1,0]
	v_pk_mul_f32 v[14:15], v[14:15], v[44:45] op_sel_hi:[1,0]
	v_pk_mul_f32 v[12:13], v[12:13], v[44:45] op_sel_hi:[1,0]
	v_pk_mul_f32 v[70:71], v[70:71], v[44:45] op_sel_hi:[1,0]
	v_pk_mul_f32 v[68:69], v[68:69], v[44:45] op_sel_hi:[1,0]
	v_pk_mul_f32 v[10:11], v[10:11], v[44:45] op_sel_hi:[1,0]
	v_pk_mul_f32 v[8:9], v[8:9], v[44:45] op_sel_hi:[1,0]
	s_branch .LBB0_453

.LBB0_453:
	v_fmamk_f32 v41, v41, 0x3e38aa3b, v86
	v_fmamk_f32 v40, v40, 0x3e38aa3b, v86
	v_exp_f32_e32 v44, v41
	v_fmamk_f32 v41, v42, 0x3e38aa3b, v86
	v_fmamk_f32 v42, v43, 0x3e38aa3b, v86
	v_exp_f32_e32 v40, v40
	v_exp_f32_e32 v41, v41
	v_exp_f32_e32 v45, v42
	s_min_u32 s44, s46, 4
	s_lshl_b32 s44, s44, 4
	s_add_i32 s44, s44, s37
	v_pk_add_f32 v[42:43], v[40:41], v[44:45]
	v_cvt_pk_bf16_f32 v40, v40, v44
	v_cvt_pk_bf16_f32 v41, v41, v45
	v_add_u32_e32 v84, 32, v84
	s_nop 1
	s_setprio 1
	v_mfma_f32_16x16x16_bf16 v[48:51], v[32:33], v[40:41], v[48:51]
	v_mfma_f32_16x16x16_bf16 v[12:15], v[34:35], v[40:41], v[12:15]
	v_mfma_f32_16x16x16_bf16 v[68:71], v[36:37], v[40:41], v[68:71]
	v_mfma_f32_16x16x16_bf16 v[8:11], v[38:39], v[40:41], v[8:11]
	s_nop 7
	s_setprio 0
	v_or_b32_e32 v32, s44, v149
	v_lshl_add_u32 v32, v32, 4, s9
	v_add_u32_e32 v33, s44, v194
	v_med3_i32 v32, v32, 0, v244
	v_lshl_add_u32 v33, v33, 4, s9
	v_med3_i32 v34, v33, 0, v244
	v_mul_u32_u24_e32 v176, 0x2800, v32
	v_lshl_add_u64 v[32:33], v[72:73], 0, v[176:177]
	v_mul_u32_u24_e32 v176, 0x2800, v34
	v_add_f32_e32 v42, v42, v43
	v_lshl_add_u64 v[36:37], v[74:75], 0, v[176:177]
	v_add_f32_e32 v87, v87, v42
	global_load_dwordx4 v[40:43], v[32:33], off offset:2560
	global_load_dwordx4 v[44:47], v[32:33], off offset:2624
	s_nop 0
	global_load_dwordx4 v[32:35], v[36:37], off offset:16
	s_nop 0
	global_load_dwordx4 v[36:39], v[36:37], off
	s_waitcnt vmcnt(8)
	ds_write_b128 v211, v[64:67]
	ds_write_b128 v211, v[60:63] offset:16
	ds_read_b64_tr_b16 v[60:61], v212
	ds_read_b64_tr_b16 v[62:63], v212 offset:32
	ds_read_b64_tr_b16 v[64:65], v212 offset:64
	ds_read_b64_tr_b16 v[66:67], v212 offset:96
	s_nop 1
	s_setprio 1
	v_mfma_f32_16x16x32_bf16 v[88:91], v[52:55], v[0:3], 0
	v_mfma_f32_16x16x32_bf16 v[88:91], v[56:59], v[4:7], v[88:91]
	s_nop 7
	s_setprio 0
	v_add_u32_e32 v52, 0xa0, v83
	v_cmp_gt_u32_e32 vcc, s16, v52
	v_cmp_lt_i32_e64 s[44:45], -1, v84
	v_add_u32_e32 v53, 32, v83
	s_and_b64 vcc, s[44:45], vcc
	v_cndmask_b32_e32 v52, v245, v88, vcc
	v_cmp_lt_u32_e32 vcc, s17, v53
	v_cmp_lt_i32_e64 s[44:45], -2, v84
	s_and_b64 vcc, s[44:45], vcc
	v_add_u32_e32 v54, 0xa2, v83
	v_cndmask_b32_e32 v53, v245, v89, vcc
	v_cmp_gt_u32_e32 vcc, s16, v54
	v_cmp_lt_i32_e64 s[44:45], -3, v84
	s_and_b64 vcc, s[44:45], vcc
	v_add_u32_e32 v55, 0xa3, v83
	v_cndmask_b32_e32 v54, v245, v90, vcc
	v_cmp_gt_u32_e32 vcc, s16, v55
	v_cmp_lt_i32_e64 s[44:45], -4, v84
	s_and_b64 vcc, s[44:45], vcc
	v_cndmask_b32_e32 v55, v245, v91, vcc
	v_max_f32_e32 v56, v55, v55
	v_max_f32_e32 v57, v54, v54
	v_max_f32_e32 v56, v57, v56
	v_max3_f32 v56, v52, v53, v56
	ds_swizzle_b32 v57, v56 offset:swizzle(SWAP,16)
	s_waitcnt lgkmcnt(0)
	v_max_f32_e32 v57, v57, v57
	v_max_f32_e32 v56, v56, v57
	v_mov_b32_e32 v57, v56
	s_nop 1
	v_permlane32_swap_b32_e32 v56, v57
	v_max_f32_e32 v57, v57, v57
	v_max_f32_e32 v56, v56, v56
	v_max_f32_e32 v56, v56, v57
	v_mul_f32_e32 v56, 0x3e38aa3b, v56
	v_cmp_gt_f32_e32 vcc, v56, v85
	s_cbranch_vccz .LBB0_447
	s_nop 0
	v_cndmask_b32_e32 v57, v82, v56, vcc
	v_sub_f32_e32 v56, v82, v57
	v_exp_f32_e32 v56, v56
	v_xor_b32_e32 v86, 0x80000000, v57
	v_mov_b32_e32 v82, v57
	v_mul_f32_e32 v87, v87, v56
	v_pk_mul_f32 v[50:51], v[50:51], v[56:57] op_sel_hi:[1,0]
	v_pk_mul_f32 v[48:49], v[48:49], v[56:57] op_sel_hi:[1,0]
	v_pk_mul_f32 v[14:15], v[14:15], v[56:57] op_sel_hi:[1,0]
	v_pk_mul_f32 v[12:13], v[12:13], v[56:57] op_sel_hi:[1,0]
	v_pk_mul_f32 v[70:71], v[70:71], v[56:57] op_sel_hi:[1,0]
	v_pk_mul_f32 v[68:69], v[68:69], v[56:57] op_sel_hi:[1,0]
	v_pk_mul_f32 v[10:11], v[10:11], v[56:57] op_sel_hi:[1,0]
	v_pk_mul_f32 v[8:9], v[8:9], v[56:57] op_sel_hi:[1,0]
	s_branch .LBB0_447

.LBB0_458:
	v_fmamk_f32 v53, v53, 0x3e38aa3b, v81
	v_fmamk_f32 v52, v52, 0x3e38aa3b, v81
	v_exp_f32_e32 v56, v53
	v_fmamk_f32 v53, v54, 0x3e38aa3b, v81
	v_fmac_f32_e32 v81, 0x3e38aa3b, v55
	v_exp_f32_e32 v52, v52
	v_exp_f32_e32 v53, v53
	v_exp_f32_e32 v57, v81
	s_add_i32 s36, s36, 3
	s_andn2_b64 vcc, exec, s[0:1]
	s_add_i32 s30, s30, 48
	v_pk_add_f32 v[54:55], v[52:53], v[56:57]
	v_cvt_pk_bf16_f32 v52, v52, v56
	v_cvt_pk_bf16_f32 v53, v53, v57
	s_nop 0
	v_add_f32_e32 v54, v54, v55
	v_add_f32_e32 v81, v82, v54
	s_nop 1
	s_setprio 1
	v_mfma_f32_16x16x16_bf16 v[48:51], v[60:61], v[52:53], v[48:51]
	v_mfma_f32_16x16x16_bf16 v[68:71], v[62:63], v[52:53], v[68:71]
	v_mfma_f32_16x16x16_bf16 v[12:15], v[64:65], v[52:53], v[12:15]
	v_mfma_f32_16x16x16_bf16 v[8:11], v[66:67], v[52:53], v[8:11]
	s_nop 7
	s_setprio 0
	s_cbranch_vccz .LBB0_466
.LBB0_459:
	s_add_i32 s31, s4, s30
	s_add_i32 s0, s31, 0xa0
	s_cmp_lt_u32 s36, 7
	s_cselect_b32 s0, s0, 0x80
	s_add_i32 s0, s0, s5
	v_or_b32_e32 v52, s0, v149
	v_lshl_add_u32 v52, v52, 4, s10
	v_add_u32_e32 v53, s0, v194
	v_med3_i32 v52, v52, 0, v244
	v_lshl_add_u32 v53, v53, 4, s10
	v_med3_i32 v53, v53, 0, v244
	v_mul_u32_u24_e32 v176, 0x2800, v52
	v_lshl_add_u64 v[56:57], v[72:73], 0, v[176:177]
	v_mul_u32_u24_e32 v176, 0x2800, v53
	v_lshl_add_u64 v[64:65], v[74:75], 0, v[176:177]
	global_load_dwordx4 v[52:55], v[56:57], off offset:2560
	s_nop 0
	global_load_dwordx4 v[56:59], v[56:57], off offset:2624
	s_nop 0
	global_load_dwordx4 v[60:63], v[64:65], off offset:16
	s_nop 0
	global_load_dwordx4 v[64:67], v[64:65], off
	s_waitcnt vmcnt(6)
	ds_write_b128 v211, v[28:31]
	ds_write_b128 v211, v[16:19] offset:16
	v_add_u32_e32 v77, s30, v78
	ds_read_b64_tr_b16 v[16:17], v212
	ds_read_b64_tr_b16 v[18:19], v212 offset:32
	ds_read_b64_tr_b16 v[28:29], v212 offset:64
	ds_read_b64_tr_b16 v[30:31], v212 offset:96
	v_add_u32_e32 v79, s30, v195
	s_waitcnt vmcnt(4)
	s_nop 1
	s_setprio 1
	v_mfma_f32_16x16x32_bf16 v[82:85], v[20:23], v[0:3], 0
	v_mfma_f32_16x16x32_bf16 v[82:85], v[24:27], v[4:7], v[82:85]
	s_nop 7
	s_setprio 0
	v_add_u32_e32 v20, 0x80, v77
	v_cmp_gt_u32_e32 vcc, s16, v20
	v_cmp_lt_i32_e64 s[44:45], -1, v79
	s_and_b64 vcc, s[44:45], vcc
	v_cndmask_b32_e32 v20, v245, v82, vcc
	v_cmp_lt_u32_e32 vcc, s17, v77
	v_cmp_lt_i32_e64 s[44:45], -2, v79
	s_and_b64 vcc, s[44:45], vcc
	v_add_u32_e32 v22, 0x82, v77
	v_cndmask_b32_e32 v21, v245, v83, vcc
	v_cmp_gt_u32_e32 vcc, s16, v22
	v_cmp_lt_i32_e64 s[44:45], -3, v79
	s_and_b64 vcc, s[44:45], vcc
	v_add_u32_e32 v23, 0x83, v77
	v_cndmask_b32_e32 v22, v245, v84, vcc
	v_cmp_gt_u32_e32 vcc, s16, v23
	v_cmp_lt_i32_e64 s[44:45], -4, v79
	s_and_b64 vcc, s[44:45], vcc
	v_cndmask_b32_e32 v23, v245, v85, vcc
	v_max_f32_e32 v24, v23, v23
	v_max_f32_e32 v25, v22, v22
	v_max_f32_e32 v24, v25, v24
	v_max3_f32 v24, v20, v21, v24
	ds_swizzle_b32 v25, v24 offset:swizzle(SWAP,16)
	v_add_f32_e32 v80, 0x41000000, v76
	s_waitcnt lgkmcnt(0)
	v_max_f32_e32 v25, v25, v25
	v_max_f32_e32 v24, v24, v25
	v_mov_b32_e32 v25, v24
	s_nop 1
	v_permlane32_swap_b32_e32 v24, v25
	v_max_f32_e32 v25, v25, v25
	v_max_f32_e32 v24, v24, v24
	v_max_f32_e32 v24, v24, v25
	v_mul_f32_e32 v24, 0x3e38aa3b, v24
	v_cmp_gt_f32_e32 vcc, v24, v80
	s_cbranch_vccz .LBB0_461
	s_nop 0
	v_cndmask_b32_e32 v25, v76, v24, vcc
	v_sub_f32_e32 v24, v76, v25
	v_exp_f32_e32 v24, v24
	v_add_f32_e32 v80, 0x41000000, v25
	v_mov_b32_e32 v76, v25
	v_mul_f32_e32 v81, v81, v24
	v_pk_mul_f32 v[10:11], v[10:11], v[24:25] op_sel_hi:[1,0]
	v_pk_mul_f32 v[8:9], v[8:9], v[24:25] op_sel_hi:[1,0]
	v_pk_mul_f32 v[14:15], v[14:15], v[24:25] op_sel_hi:[1,0]
	v_pk_mul_f32 v[12:13], v[12:13], v[24:25] op_sel_hi:[1,0]
	v_pk_mul_f32 v[70:71], v[70:71], v[24:25] op_sel_hi:[1,0]
	v_pk_mul_f32 v[68:69], v[68:69], v[24:25] op_sel_hi:[1,0]
	v_pk_mul_f32 v[50:51], v[50:51], v[24:25] op_sel_hi:[1,0]
	v_pk_mul_f32 v[48:49], v[48:49], v[24:25] op_sel_hi:[1,0]
.LBB0_461:
	v_fma_f32 v21, v21, s18, -v76
	v_fma_f32 v20, v20, s18, -v76
	v_exp_f32_e32 v24, v21
	v_fma_f32 v21, v22, s18, -v76
	v_fma_f32 v22, v23, s18, -v76
	s_cmp_gt_u32 s36, 5
	v_exp_f32_e32 v20, v20
	v_exp_f32_e32 v21, v21
	v_exp_f32_e32 v25, v22
	s_cselect_b64 s[0:1], -1, 0
	s_addk_i32 s31, 0xb0
	s_cmp_lt_u32 s36, 6
	s_cselect_b32 s31, s31, 0x80
	s_add_i32 s31, s31, s5
	v_pk_add_f32 v[22:23], v[20:21], v[24:25]
	v_cvt_pk_bf16_f32 v20, v20, v24
	v_cvt_pk_bf16_f32 v21, v21, v25
	s_nop 0
	s_nop 1
	s_setprio 1
	v_mfma_f32_16x16x16_bf16 v[48:51], v[16:17], v[20:21], v[48:51]
	v_mfma_f32_16x16x16_bf16 v[68:71], v[18:19], v[20:21], v[68:71]
	v_mfma_f32_16x16x16_bf16 v[12:15], v[28:29], v[20:21], v[12:15]
	v_mfma_f32_16x16x16_bf16 v[8:11], v[30:31], v[20:21], v[8:11]
	s_nop 7
	s_setprio 0
	v_or_b32_e32 v16, s31, v149
	v_lshl_add_u32 v16, v16, 4, s10
	v_add_u32_e32 v17, s31, v194
	v_med3_i32 v16, v16, 0, v244
	v_lshl_add_u32 v17, v17, 4, s10
	v_med3_i32 v18, v17, 0, v244
	v_mul_u32_u24_e32 v176, 0x2800, v16
	v_lshl_add_u64 v[16:17], v[72:73], 0, v[176:177]
	v_mul_u32_u24_e32 v176, 0x2800, v18
	v_add_f32_e32 v22, v22, v23
	v_lshl_add_u64 v[28:29], v[74:75], 0, v[176:177]
	v_add_f32_e32 v82, v81, v22
	global_load_dwordx4 v[20:23], v[16:17], off offset:2560
	global_load_dwordx4 v[24:27], v[16:17], off offset:2624
	s_nop 0
	global_load_dwordx4 v[16:19], v[28:29], off offset:16
	s_nop 0
	global_load_dwordx4 v[28:31], v[28:29], off
	ds_write_b128 v211, v[36:39]
	ds_write_b128 v211, v[32:35] offset:16
	ds_read_b64_tr_b16 v[32:33], v212
	ds_read_b64_tr_b16 v[34:35], v212 offset:32
	ds_read_b64_tr_b16 v[36:37], v212 offset:64
	ds_read_b64_tr_b16 v[38:39], v212 offset:96
	v_add_u32_e32 v81, 16, v79
	s_nop 1
	s_setprio 1
	v_mfma_f32_16x16x32_bf16 v[84:87], v[40:43], v[0:3], 0
	v_mfma_f32_16x16x32_bf16 v[84:87], v[44:47], v[4:7], v[84:87]
	s_nop 7
	s_setprio 0
	v_add_u32_e32 v40, 0x90, v77
	v_cmp_gt_u32_e32 vcc, s16, v40
	v_cmp_lt_i32_e64 s[44:45], -1, v81
	v_add_u32_e32 v41, 16, v77
	s_and_b64 vcc, s[44:45], vcc
	v_cndmask_b32_e32 v40, v245, v84, vcc
	v_cmp_lt_u32_e32 vcc, s17, v41
	v_cmp_lt_i32_e64 s[44:45], -2, v81
	s_and_b64 vcc, s[44:45], vcc
	v_add_u32_e32 v42, 0x92, v77
	v_cndmask_b32_e32 v41, v245, v85, vcc
	v_cmp_gt_u32_e32 vcc, s16, v42
	v_cmp_lt_i32_e64 s[44:45], -3, v81
	s_and_b64 vcc, s[44:45], vcc
	v_add_u32_e32 v43, 0x93, v77
	v_cndmask_b32_e32 v42, v245, v86, vcc
	v_cmp_gt_u32_e32 vcc, s16, v43
	v_cmp_lt_i32_e64 s[44:45], -4, v81
	s_and_b64 vcc, s[44:45], vcc
	v_cndmask_b32_e32 v43, v245, v87, vcc
	v_max_f32_e32 v44, v43, v43
	v_max_f32_e32 v45, v42, v42
	v_max_f32_e32 v44, v45, v44
	v_max3_f32 v44, v40, v41, v44
	ds_swizzle_b32 v45, v44 offset:swizzle(SWAP,16)
	s_waitcnt lgkmcnt(0)
	v_max_f32_e32 v45, v45, v45
	v_max_f32_e32 v44, v44, v45
	v_mov_b32_e32 v45, v44
	s_nop 1
	v_permlane32_swap_b32_e32 v44, v45
	v_max_f32_e32 v45, v45, v45
	v_max_f32_e32 v44, v44, v44
	v_max_f32_e32 v44, v44, v45
	v_mul_f32_e32 v44, 0x3e38aa3b, v44
	v_cmp_gt_f32_e32 vcc, v44, v80
	s_cbranch_vccz .LBB0_463
	s_nop 0
	v_cndmask_b32_e32 v45, v76, v44, vcc
	v_sub_f32_e32 v44, v76, v45
	v_exp_f32_e32 v44, v44
	v_xor_b32_e32 v81, 0x80000000, v45
	v_add_f32_e32 v80, 0x41000000, v45
	v_mov_b32_e32 v76, v45
	v_mul_f32_e32 v82, v82, v44
	v_pk_mul_f32 v[50:51], v[50:51], v[44:45] op_sel_hi:[1,0]
	v_pk_mul_f32 v[48:49], v[48:49], v[44:45] op_sel_hi:[1,0]
	v_pk_mul_f32 v[70:71], v[70:71], v[44:45] op_sel_hi:[1,0]
	v_pk_mul_f32 v[68:69], v[68:69], v[44:45] op_sel_hi:[1,0]
	v_pk_mul_f32 v[14:15], v[14:15], v[44:45] op_sel_hi:[1,0]
	v_pk_mul_f32 v[12:13], v[12:13], v[44:45] op_sel_hi:[1,0]
	v_pk_mul_f32 v[10:11], v[10:11], v[44:45] op_sel_hi:[1,0]
	v_pk_mul_f32 v[8:9], v[8:9], v[44:45] op_sel_hi:[1,0]
	s_branch .LBB0_464

.LBB0_464:
	v_fmamk_f32 v41, v41, 0x3e38aa3b, v81
	v_fmamk_f32 v40, v40, 0x3e38aa3b, v81
	v_exp_f32_e32 v44, v41
	v_fmamk_f32 v41, v42, 0x3e38aa3b, v81
	v_fmamk_f32 v42, v43, 0x3e38aa3b, v81
	v_exp_f32_e32 v40, v40
	v_exp_f32_e32 v41, v41
	v_exp_f32_e32 v45, v42
	s_min_u32 s31, s36, 4
	s_lshl_b32 s31, s31, 4
	s_add_i32 s31, s31, s37
	v_pk_add_f32 v[42:43], v[40:41], v[44:45]
	v_cvt_pk_bf16_f32 v40, v40, v44
	v_cvt_pk_bf16_f32 v41, v41, v45
	v_add_u32_e32 v79, 32, v79
	s_nop 1
	s_setprio 1
	v_mfma_f32_16x16x16_bf16 v[48:51], v[32:33], v[40:41], v[48:51]
	v_mfma_f32_16x16x16_bf16 v[68:71], v[34:35], v[40:41], v[68:71]
	v_mfma_f32_16x16x16_bf16 v[12:15], v[36:37], v[40:41], v[12:15]
	v_mfma_f32_16x16x16_bf16 v[8:11], v[38:39], v[40:41], v[8:11]
	s_nop 7
	s_setprio 0
	v_or_b32_e32 v32, s31, v149
	v_lshl_add_u32 v32, v32, 4, s10
	v_add_u32_e32 v33, s31, v194
	v_med3_i32 v32, v32, 0, v244
	v_lshl_add_u32 v33, v33, 4, s10
	v_med3_i32 v34, v33, 0, v244
	v_mul_u32_u24_e32 v176, 0x2800, v32
	v_lshl_add_u64 v[32:33], v[72:73], 0, v[176:177]
	v_mul_u32_u24_e32 v176, 0x2800, v34
	v_add_f32_e32 v42, v42, v43
	v_lshl_add_u64 v[36:37], v[74:75], 0, v[176:177]
	v_add_f32_e32 v82, v82, v42
	global_load_dwordx4 v[40:43], v[32:33], off offset:2560
	global_load_dwordx4 v[44:47], v[32:33], off offset:2624
	s_nop 0
	global_load_dwordx4 v[32:35], v[36:37], off offset:16
	s_nop 0
	global_load_dwordx4 v[36:39], v[36:37], off
	s_waitcnt vmcnt(8)
	ds_write_b128 v211, v[64:67]
	ds_write_b128 v211, v[60:63] offset:16
	ds_read_b64_tr_b16 v[60:61], v212
	ds_read_b64_tr_b16 v[62:63], v212 offset:32
	ds_read_b64_tr_b16 v[64:65], v212 offset:64
	ds_read_b64_tr_b16 v[66:67], v212 offset:96
	s_nop 1
	s_setprio 1
	v_mfma_f32_16x16x32_bf16 v[84:87], v[52:55], v[0:3], 0
	v_mfma_f32_16x16x32_bf16 v[84:87], v[56:59], v[4:7], v[84:87]
	s_nop 7
	s_setprio 0
	v_add_u32_e32 v52, 0xa0, v77
	v_cmp_gt_u32_e32 vcc, s16, v52
	v_cmp_lt_i32_e64 s[44:45], -1, v79
	v_add_u32_e32 v53, 32, v77
	s_and_b64 vcc, s[44:45], vcc
	v_cndmask_b32_e32 v52, v245, v84, vcc
	v_cmp_lt_u32_e32 vcc, s17, v53
	v_cmp_lt_i32_e64 s[44:45], -2, v79
	s_and_b64 vcc, s[44:45], vcc
	v_add_u32_e32 v54, 0xa2, v77
	v_cndmask_b32_e32 v53, v245, v85, vcc
	v_cmp_gt_u32_e32 vcc, s16, v54
	v_cmp_lt_i32_e64 s[44:45], -3, v79
	s_and_b64 vcc, s[44:45], vcc
	v_add_u32_e32 v55, 0xa3, v77
	v_cndmask_b32_e32 v54, v245, v86, vcc
	v_cmp_gt_u32_e32 vcc, s16, v55
	v_cmp_lt_i32_e64 s[44:45], -4, v79
	s_and_b64 vcc, s[44:45], vcc
	v_cndmask_b32_e32 v55, v245, v87, vcc
	v_max_f32_e32 v56, v55, v55
	v_max_f32_e32 v57, v54, v54
	v_max_f32_e32 v56, v57, v56
	v_max3_f32 v56, v52, v53, v56
	ds_swizzle_b32 v57, v56 offset:swizzle(SWAP,16)
	s_waitcnt lgkmcnt(0)
	v_max_f32_e32 v57, v57, v57
	v_max_f32_e32 v56, v56, v57
	v_mov_b32_e32 v57, v56
	s_nop 1
	v_permlane32_swap_b32_e32 v56, v57
	v_max_f32_e32 v57, v57, v57
	v_max_f32_e32 v56, v56, v56
	v_max_f32_e32 v56, v56, v57
	v_mul_f32_e32 v56, 0x3e38aa3b, v56
	v_cmp_gt_f32_e32 vcc, v56, v80
	s_cbranch_vccz .LBB0_458
	s_nop 0
	v_cndmask_b32_e32 v57, v76, v56, vcc
	v_sub_f32_e32 v56, v76, v57
	v_exp_f32_e32 v56, v56
	v_xor_b32_e32 v81, 0x80000000, v57
	v_mov_b32_e32 v76, v57
	v_mul_f32_e32 v82, v82, v56
	v_pk_mul_f32 v[50:51], v[50:51], v[56:57] op_sel_hi:[1,0]
	v_pk_mul_f32 v[48:49], v[48:49], v[56:57] op_sel_hi:[1,0]
	v_pk_mul_f32 v[70:71], v[70:71], v[56:57] op_sel_hi:[1,0]
	v_pk_mul_f32 v[68:69], v[68:69], v[56:57] op_sel_hi:[1,0]
	v_pk_mul_f32 v[14:15], v[14:15], v[56:57] op_sel_hi:[1,0]
	v_pk_mul_f32 v[12:13], v[12:13], v[56:57] op_sel_hi:[1,0]
	v_pk_mul_f32 v[10:11], v[10:11], v[56:57] op_sel_hi:[1,0]
	v_pk_mul_f32 v[8:9], v[8:9], v[56:57] op_sel_hi:[1,0]
	s_branch .LBB0_458

.LBB0_476:
	s_waitcnt vmcnt(15)
	s_setprio 1
	v_mfma_f32_16x16x32_bf16 v[72:75], v[72:75], v[8:11], 0
	s_setprio 0
	v_add_u32_e32 v155, s29, v152
	v_add_u32_e32 v147, 49, v155
	v_cmp_lt_i32_e64 s[46:47], v147, v191
	s_waitcnt vmcnt(14)
	s_setprio 1
	v_mfma_f32_16x16x32_bf16 v[68:71], v[68:71], v[0:3], v[72:75]
	s_setprio 0
	v_add_u32_e32 v146, 48, v155
	v_cmp_lt_i32_e64 s[50:51], -1, v146
	s_add_i32 s0, s29, 16
	v_add_u32_e32 v74, 50, v155
	v_cmp_lt_i32_e64 s[48:49], v74, v191
	s_nop 2
	v_mul_f32_e32 v72, 0x3e000000, v68
	v_mul_f32_e64 v73, |v72|, s14
	v_exp_f32_e32 v73, v73
	v_max_f32_e32 v72, 0, v72
	s_cmp_gt_i32 s30, 1
	s_cselect_b32 s4, s0, 0
	v_add_f32_e32 v73, 1.0, v73
	v_cmp_gt_f32_e32 vcc, s13, v73
	s_and_b64 s[46:47], s[50:51], s[46:47]
	s_and_b64 s[48:49], s[50:51], s[48:49]
	v_cndmask_b32_e64 v74, 0, 32, vcc
	v_ldexp_f32 v73, v73, v74
	v_log_f32_e32 v73, v73
	v_add_u32_e32 v74, 51, v155
	v_cmp_lt_i32_e64 s[52:53], v74, v191
	v_cndmask_b32_e32 v147, 0, v247, vcc
	v_mul_f32_e32 v74, 0x3f317217, v73
	v_fma_f32 v74, v73, s22, -v74
	v_fmac_f32_e32 v74, 0x3377d1cf, v73
	v_fmac_f32_e32 v74, 0x3f317217, v73
	v_cmp_lt_f32_e64 s[54:55], |v73|, s23
	v_cmp_lt_u32_e32 vcc, v146, v191
	s_and_b64 s[50:51], s[50:51], s[52:53]
	v_cndmask_b32_e64 v73, v73, v74, s[54:55]
	v_mul_f32_e32 v74, 0x3e000000, v69
	v_mul_f32_e64 v75, |v74|, s14
	v_exp_f32_e32 v75, v75
	v_sub_f32_e32 v73, v73, v147
	v_add_f32_e32 v72, v72, v73
	v_max_f32_e32 v74, 0, v74
	v_add_f32_e32 v73, 1.0, v75
	v_cmp_gt_f32_e64 s[54:55], s13, v73
	s_waitcnt vmcnt(11)
	s_setprio 1
	v_mfma_f32_16x16x32_bf16 v[52:55], v[52:55], v[4:7], 0
	s_setprio 0
	v_fma_f32 v68, v68, s21, -v72
	v_cndmask_b32_e64 v75, 0, 32, s[54:55]
	v_ldexp_f32 v73, v73, v75
	v_log_f32_e32 v73, v73
	v_cndmask_b32_e64 v161, 0, v247, s[54:55]
	v_cndmask_b32_e64 v75, 0, -v72, vcc
	s_waitcnt vmcnt(10)
	s_setprio 1
	v_mfma_f32_16x16x32_bf16 v[48:51], v[48:51], v[12:15], v[52:55]
	s_setprio 0
	v_mul_f32_e32 v146, 0x3f317217, v73
	v_fma_f32 v146, v73, s22, -v146
	v_fmac_f32_e32 v146, 0x3377d1cf, v73
	v_fmac_f32_e32 v146, 0x3f317217, v73
	v_cmp_lt_f32_e64 s[56:57], |v73|, s23
	s_nop 2
	v_mul_f32_e32 v54, 0x3e000000, v48
	v_mul_f32_e64 v52, |v54|, s14
	v_cndmask_b32_e64 v73, v73, v146, s[56:57]
	v_mul_f32_e32 v146, 0x3e000000, v70
	v_mul_f32_e64 v147, |v146|, s14
	v_exp_f32_e32 v147, v147
	v_sub_f32_e32 v73, v73, v161
	v_add_f32_e32 v73, v74, v73
	v_max_f32_e32 v146, 0, v146
	v_add_f32_e32 v74, 1.0, v147
	v_cmp_gt_f32_e64 s[54:55], s13, v74
	v_exp_f32_e32 v52, v52
	v_fma_f32 v69, v69, s21, -v73
	v_cndmask_b32_e64 v147, 0, 32, s[54:55]
	v_ldexp_f32 v74, v74, v147
	v_log_f32_e32 v74, v74
	v_cndmask_b32_e64 v167, 0, v247, s[54:55]
	v_cndmask_b32_e64 v147, 0, -v73, s[46:47]
	v_add_f32_e32 v52, 1.0, v52
	v_mul_f32_e32 v161, 0x3f317217, v74
	v_fma_f32 v161, v74, s22, -v161
	v_fmac_f32_e32 v161, 0x3377d1cf, v74
	v_fmac_f32_e32 v161, 0x3f317217, v74
	v_cmp_lt_f32_e64 s[56:57], |v74|, s23
	v_mad_i64_i32 v[84:85], s[0:1], s4, v246, v[162:163]
	s_nop 0
	v_cndmask_b32_e64 v74, v74, v161, s[56:57]
	v_mul_f32_e32 v161, 0x3e000000, v71
	v_mul_f32_e64 v166, |v161|, s14
	v_exp_f32_e32 v166, v166
	v_sub_f32_e32 v74, v74, v167
	v_add_f32_e32 v74, v146, v74
	v_max_f32_e32 v161, 0, v161
	v_add_f32_e32 v146, 1.0, v166
	v_cmp_gt_f32_e64 s[54:55], s13, v146
	v_fma_f32 v70, v70, s21, -v74
	v_mad_i64_i32 v[88:89], s[0:1], s4, v246, v[164:165]
	v_cndmask_b32_e64 v166, 0, 32, s[54:55]
	v_ldexp_f32 v146, v146, v166
	v_log_f32_e32 v146, v146
	v_cndmask_b32_e64 v166, 0, -v74, s[48:49]
	global_load_dwordx4 v[140:143], v[84:85], off
	global_load_dwordx4 v[136:139], v[84:85], off offset:64
	global_load_dwordx4 v[92:95], v[88:89], off offset:16
	global_load_dwordx4 v[96:99], v[88:89], off
	global_load_dwordx4 v[104:107], v[84:85], off offset:128
	global_load_dwordx4 v[100:103], v[84:85], off offset:192
	s_nop 0
	global_load_dwordx4 v[84:87], v[88:89], off offset:144
	s_nop 0
	global_load_dwordx4 v[88:91], v[88:89], off offset:128
	v_mul_f32_e32 v73, 0x3e000000, v51
	v_mul_f32_e32 v167, 0x3f317217, v146
	v_fma_f32 v167, v146, s22, -v167
	v_fmac_f32_e32 v167, 0x3377d1cf, v146
	v_fmac_f32_e32 v167, 0x3f317217, v146
	v_cmp_lt_f32_e64 s[56:57], |v146|, s23
	v_mul_f32_e64 v74, |v73|, s14
	v_exp_f32_e32 v74, v74
	v_cndmask_b32_e64 v146, v146, v167, s[56:57]
	v_cndmask_b32_e64 v167, 0, v247, s[54:55]
	v_sub_f32_e32 v146, v146, v167
	v_add_f32_e32 v146, v161, v146
	v_cndmask_b32_e64 v161, 0, -v146, s[50:51]
	v_add_f32_e32 v167, v161, v166
	v_add_f32_e32 v147, v147, v167
	v_add_f32_e32 v166, v75, v147
	ds_swizzle_b32 v170, v166 offset:swizzle(SWAP,16)
	v_mov_b32_e32 v75, v166
	v_mov_b32_e32 v168, v166
	s_nop 1
	v_permlane32_swap_b32_e32 v75, v168
	v_cmp_eq_u32_e64 s[52:53], v75, v166
	s_waitcnt lgkmcnt(0)
	v_mov_b32_e32 v169, v170
	v_fma_f32 v71, v71, s21, -v146
	v_cndmask_b32_e64 v168, v75, v168, s[52:53]
	v_mov_b32_e32 v75, v170
	s_nop 1
	v_permlane32_swap_b32_e32 v75, v169
	v_cmp_eq_u32_e64 s[52:53], v75, v170
	v_max_f32_e32 v73, 0, v73
	v_max_f32_e32 v54, 0, v54
	v_cndmask_b32_e64 v172, v75, v169, s[52:53]
	v_cndmask_b32_e64 v75, 0, v170, s[40:41]
	v_cndmask_b32_e64 v169, 0, v168, s[42:43]
	v_add_f32_e32 v75, v75, v169
	v_cndmask_b32_e64 v169, 0, v172, s[44:45]
	v_add_f32_e32 v75, v169, v75
	v_add_f32_e32 v75, v144, v75
	v_add_f32_e32 v70, v70, v75
	v_add_f32_e32 v70, v161, v70
	v_add_f32_e32 v68, v68, v75
	v_mul_f32_e32 v70, 0x3fb8aa3b, v70
	v_add_f32_e32 v68, v147, v68
	v_add_f32_e32 v69, v69, v75
	v_exp_f32_e32 v70, v70
	v_add_f32_e32 v71, v71, v75
	v_mul_f32_e32 v68, 0x3fb8aa3b, v68
	v_add_f32_e32 v69, v167, v69
	v_add_f32_e32 v71, 0, v71
	v_exp_f32_e32 v68, v68
	v_mul_f32_e32 v69, 0x3fb8aa3b, v69
	v_mul_f32_e32 v71, 0x3fb8aa3b, v71
	v_exp_f32_e32 v69, v69
	v_exp_f32_e32 v71, v71
	v_cmp_gt_f32_e64 s[52:53], s13, v52
	v_cndmask_b32_e64 v55, 0, v70, s[48:49]
	v_cndmask_b32_e32 v68, 0, v68, vcc
	v_cndmask_b32_e64 v70, 0, 32, s[52:53]
	v_ldexp_f32 v52, v52, v70
	v_log_f32_e32 v70, v52
	v_cndmask_b32_e64 v53, 0, v69, s[46:47]
	v_cndmask_b32_e64 v69, 0, v71, s[50:51]
	v_cvt_pk_bf16_f32 v52, v68, v53
	v_mul_f32_e32 v68, 0x3e000000, v49
	v_cvt_pk_bf16_f32 v53, v55, v69
	v_mul_f32_e64 v69, |v68|, s14
	v_exp_f32_e32 v69, v69
	v_mul_f32_e32 v55, 0x3f317217, v70
	v_fma_f32 v55, v70, s22, -v55
	v_fmac_f32_e32 v55, 0x3377d1cf, v70
	v_fmac_f32_e32 v55, 0x3f317217, v70
	v_cmp_lt_f32_e64 s[54:55], |v70|, s23
	v_add_f32_e32 v69, 1.0, v69
	v_mul_f32_e32 v71, 0x3e000000, v50
	v_cndmask_b32_e64 v55, v70, v55, s[54:55]
	v_cndmask_b32_e64 v70, 0, v247, s[52:53]
	v_cmp_gt_f32_e64 s[52:53], s13, v69
	v_sub_f32_e32 v55, v55, v70
	v_mul_f32_e64 v72, |v71|, s14
	v_cndmask_b32_e64 v70, 0, 32, s[52:53]
	v_ldexp_f32 v69, v69, v70
	v_log_f32_e32 v69, v69
	v_exp_f32_e32 v72, v72
	v_max_f32_e32 v71, 0, v71
	v_max_f32_e32 v68, 0, v68
	v_mul_f32_e32 v70, 0x3f317217, v69
	v_fma_f32 v70, v69, s22, -v70
	v_fmac_f32_e32 v70, 0x3377d1cf, v69
	v_fmac_f32_e32 v70, 0x3f317217, v69
	v_cmp_lt_f32_e64 s[54:55], |v69|, s23
	v_add_f32_e32 v54, v54, v55
	v_cndmask_b32_e64 v55, 0, -v54, vcc
	v_cndmask_b32_e64 v69, v69, v70, s[54:55]
	v_cndmask_b32_e64 v70, 0, v247, s[52:53]
	v_sub_f32_e32 v69, v69, v70
	v_add_f32_e32 v70, 1.0, v72
	v_cmp_gt_f32_e64 s[52:53], s13, v70
	v_add_f32_e32 v68, v68, v69
	v_cndmask_b32_e64 v69, 0, -v68, s[46:47]
	v_cndmask_b32_e64 v72, 0, 32, s[52:53]
	v_ldexp_f32 v70, v70, v72
	v_log_f32_e32 v70, v70
	s_waitcnt vmcnt(15)
	s_setprio 1
	v_mfma_f32_16x16x32_bf16 v[80:83], v[80:83], v[8:11], 0
	s_setprio 0
	v_fma_f32 v48, v48, s21, -v54
	v_add_u32_e32 v161, 32, v155
	v_mul_f32_e32 v72, 0x3f317217, v70
	v_fma_f32 v72, v70, s22, -v72
	v_fmac_f32_e32 v72, 0x3377d1cf, v70
	v_fmac_f32_e32 v72, 0x3f317217, v70
	v_cmp_lt_f32_e64 s[54:55], |v70|, s23
	s_waitcnt vmcnt(14)
	s_setprio 1
	v_mfma_f32_16x16x32_bf16 v[192:195], v[76:79], v[0:3], v[80:83]
	s_setprio 0
	v_add_u32_e32 v78, 34, v155
	v_cndmask_b32_e64 v70, v70, v72, s[54:55]
	v_cndmask_b32_e64 v72, 0, v247, s[52:53]
	v_sub_f32_e32 v70, v70, v72
	v_add_f32_e32 v72, 1.0, v74
	v_cmp_gt_f32_e64 s[52:53], s13, v72
	v_add_f32_e32 v70, v71, v70
	v_cndmask_b32_e64 v71, 0, -v70, s[48:49]
	v_cndmask_b32_e64 v74, 0, 32, s[52:53]
	v_ldexp_f32 v72, v72, v74
	v_log_f32_e32 v72, v72
	v_fma_f32 v50, v50, s21, -v70
	v_mul_f32_e32 v76, 0x3e000000, v192
	v_mul_f32_e64 v77, |v76|, s14
	v_mul_f32_e32 v74, 0x3f317217, v72
	v_fma_f32 v74, v72, s22, -v74
	v_fmac_f32_e32 v74, 0x3377d1cf, v72
	v_fmac_f32_e32 v74, 0x3f317217, v72
	v_cmp_lt_f32_e64 s[54:55], |v72|, s23
	v_exp_f32_e32 v77, v77
	v_max_f32_e32 v76, 0, v76
	v_cndmask_b32_e64 v72, v72, v74, s[54:55]
	v_cndmask_b32_e64 v74, 0, v247, s[52:53]
	v_sub_f32_e32 v72, v72, v74
	v_add_f32_e32 v72, v73, v72
	v_cndmask_b32_e64 v73, 0, -v72, s[50:51]
	v_add_f32_e32 v71, v73, v71
	v_add_f32_e32 v69, v69, v71
	v_add_f32_e32 v167, v55, v69
	ds_swizzle_b32 v171, v167 offset:swizzle(SWAP,16)
	v_mov_b32_e32 v55, v167
	v_mov_b32_e32 v74, v167
	s_nop 1
	v_permlane32_swap_b32_e32 v55, v74
	v_cmp_eq_u32_e64 s[52:53], v55, v167
	v_add_f32_e32 v77, 1.0, v77
	v_fma_f32 v51, v51, s21, -v72
	v_cndmask_b32_e64 v169, v55, v74, s[52:53]
	s_waitcnt lgkmcnt(0)
	v_mov_b32_e32 v55, v171
	v_mov_b32_e32 v74, v171
	s_nop 1
	v_permlane32_swap_b32_e32 v55, v74
	v_cmp_eq_u32_e64 s[52:53], v55, v171
	v_fma_f32 v49, v49, s21, -v68
	s_cmp_gt_i32 s30, 2
	v_cndmask_b32_e64 v173, v55, v74, s[52:53]
	v_cndmask_b32_e64 v55, 0, v171, s[40:41]
	v_cndmask_b32_e64 v74, 0, v169, s[42:43]
	v_add_f32_e32 v55, v55, v74
	v_cndmask_b32_e64 v74, 0, v173, s[44:45]
	v_add_f32_e32 v55, v74, v55
	v_add_f32_e32 v55, v145, v55
	v_add_f32_e32 v48, v48, v55
	v_add_f32_e32 v48, v69, v48
	v_add_f32_e32 v50, v50, v55
	v_mul_f32_e32 v48, 0x3fb8aa3b, v48
	v_add_f32_e32 v50, v73, v50
	v_exp_f32_e32 v48, v48
	v_mul_f32_e32 v50, 0x3fb8aa3b, v50
	v_exp_f32_e32 v50, v50
	v_add_f32_e32 v51, v51, v55
	v_cndmask_b32_e32 v48, 0, v48, vcc
	v_cmp_gt_f32_e32 vcc, s13, v77
	v_cndmask_b32_e64 v50, 0, v50, s[48:49]
	v_cmp_lt_i32_e64 s[48:49], v78, v191
	v_cndmask_b32_e64 v78, 0, 32, vcc
	v_ldexp_f32 v77, v77, v78
	v_log_f32_e32 v77, v77
	v_add_u32_e32 v78, 35, v155
	v_cmp_lt_i32_e64 s[52:53], v78, v191
	v_cndmask_b32_e32 v80, 0, v247, vcc
	v_mul_f32_e32 v78, 0x3f317217, v77
	v_fma_f32 v78, v77, s22, -v78
	v_fmac_f32_e32 v78, 0x3377d1cf, v77
	v_fmac_f32_e32 v78, 0x3f317217, v77
	v_cmp_lt_f32_e64 s[54:55], |v77|, s23
	v_add_f32_e32 v51, 0, v51
	v_mul_f32_e32 v51, 0x3fb8aa3b, v51
	v_cndmask_b32_e64 v77, v77, v78, s[54:55]
	v_mul_f32_e32 v78, 0x3e000000, v193
	v_mul_f32_e64 v79, |v78|, s14
	v_exp_f32_e32 v79, v79
	v_sub_f32_e32 v77, v77, v80
	v_add_f32_e32 v77, v76, v77
	v_max_f32_e32 v78, 0, v78
	v_add_f32_e32 v76, 1.0, v79
	v_cmp_gt_f32_e64 s[54:55], s13, v76
	v_exp_f32_e32 v51, v51
	v_cmp_lt_u32_e32 vcc, v161, v191
	v_cndmask_b32_e64 v79, 0, 32, s[54:55]
	v_ldexp_f32 v76, v76, v79
	v_log_f32_e32 v76, v76
	v_cndmask_b32_e64 v82, 0, v247, s[54:55]
	v_cndmask_b32_e64 v51, 0, v51, s[50:51]
	v_cmp_lt_i32_e64 s[50:51], -1, v161
	v_mul_f32_e32 v80, 0x3f317217, v76
	v_fma_f32 v80, v76, s22, -v80
	v_fmac_f32_e32 v80, 0x3377d1cf, v76
	v_fmac_f32_e32 v80, 0x3f317217, v76
	v_cmp_lt_f32_e64 s[56:57], |v76|, s23
	v_add_f32_e32 v49, v49, v55
	v_add_f32_e32 v49, v71, v49
	v_cndmask_b32_e64 v76, v76, v80, s[56:57]
	v_mul_f32_e32 v80, 0x3e000000, v194
	v_mul_f32_e64 v81, |v80|, s14
	v_exp_f32_e32 v81, v81
	v_sub_f32_e32 v76, v76, v82
	v_add_f32_e32 v83, v78, v76
	v_max_f32_e32 v80, 0, v80
	v_add_f32_e32 v76, 1.0, v81
	v_cmp_gt_f32_e64 s[54:55], s13, v76
	v_mul_f32_e32 v49, 0x3fb8aa3b, v49
	v_exp_f32_e32 v49, v49
	v_cndmask_b32_e64 v78, 0, 32, s[54:55]
	v_ldexp_f32 v76, v76, v78
	v_log_f32_e32 v76, v76
	v_cndmask_b32_e64 v161, 0, v247, s[54:55]
	s_cselect_b64 s[4:5], -1, 0
	v_add_u32_e32 v176, 33, v155
	v_mul_f32_e32 v81, 0x3f317217, v76
	v_fma_f32 v81, v76, s22, -v81
	v_fmac_f32_e32 v81, 0x3377d1cf, v76
	v_fmac_f32_e32 v81, 0x3f317217, v76
	v_cmp_lt_f32_e64 s[56:57], |v76|, s23
	v_cndmask_b32_e64 v49, 0, v49, s[46:47]
	s_and_b64 s[0:1], s[4:5], exec
	v_cndmask_b32_e64 v76, v76, v81, s[56:57]
	v_mul_f32_e32 v81, 0x3e000000, v195
	v_mul_f32_e64 v82, |v81|, s14
	v_exp_f32_e32 v82, v82
	v_sub_f32_e32 v76, v76, v161
	v_add_f32_e32 v161, v80, v76
	v_cmp_lt_i32_e64 s[46:47], v176, v191
	v_add_f32_e32 v76, 1.0, v82
	v_cmp_gt_f32_e64 s[54:55], s13, v76
	v_max_f32_e32 v81, 0, v81
	s_cselect_b32 s31, s29, 0
	v_cndmask_b32_e64 v80, 0, 32, s[54:55]
	v_ldexp_f32 v76, v76, v80
	v_log_f32_e32 v76, v76
	s_and_b64 s[46:47], s[50:51], s[46:47]
	s_and_b64 s[48:49], s[50:51], s[48:49]
	s_and_b64 s[50:51], s[50:51], s[52:53]
	v_mul_f32_e32 v82, 0x3f317217, v76
	v_fma_f32 v82, v76, s22, -v82
	v_fmac_f32_e32 v82, 0x3377d1cf, v76
	v_fmac_f32_e32 v82, 0x3f317217, v76
	v_cmp_lt_f32_e64 s[56:57], |v76|, s23
	v_cndmask_b32_e64 v80, 0, -v161, s[48:49]
	v_cndmask_b32_e64 v78, 0, -v83, s[46:47]
	v_cndmask_b32_e64 v76, v76, v82, s[56:57]
	v_cndmask_b32_e64 v82, 0, v247, s[54:55]
	v_sub_f32_e32 v76, v76, v82
	v_add_f32_e32 v81, v81, v76
	v_cndmask_b32_e64 v176, 0, -v81, s[50:51]
	v_add_f32_e32 v178, v176, v80
	v_cndmask_b32_e64 v79, 0, -v77, vcc
	v_add_f32_e32 v179, v78, v178
	v_add_f32_e32 v76, v79, v179
	ds_swizzle_b32 v78, v76 offset:swizzle(SWAP,16)
	s_waitcnt vmcnt(11)
	s_setprio 1
	v_mfma_f32_16x16x32_bf16 v[60:63], v[60:63], v[4:7], 0
	s_setprio 0
	v_mov_b32_e32 v79, v76
	v_mov_b32_e32 v80, v76
	s_nop 1
	v_permlane32_swap_b32_e32 v79, v80
	v_cmp_eq_u32_e64 s[52:53], v79, v76
	s_waitcnt lgkmcnt(0)
	v_mov_b32_e32 v82, v78
	s_waitcnt vmcnt(10)
	s_setprio 1
	v_mfma_f32_16x16x32_bf16 v[56:59], v[56:59], v[12:15], v[60:63]
	s_setprio 0
	v_cndmask_b32_e64 v80, v79, v80, s[52:53]
	v_mov_b32_e32 v79, v78
	v_cvt_pk_bf16_f32 v146, v48, v49
	v_cvt_pk_bf16_f32 v147, v50, v51
	ds_write_b128 v153, v[28:31]
	ds_write_b128 v153, v[20:23] offset:16
	v_permlane32_swap_b32_e32 v79, v82
	v_cmp_eq_u32_e64 s[52:53], v79, v78
	ds_read_b64_tr_b16 v[20:21], v190
	ds_read_b64_tr_b16 v[22:23], v190 offset:32
	ds_read_b64_tr_b16 v[28:29], v190 offset:64
	ds_read_b64_tr_b16 v[30:31], v190 offset:96
	ds_write_b128 v153, v[24:27] offset:4096
	ds_write_b128 v153, v[16:19] offset:4112
	v_cndmask_b32_e64 v82, v79, v82, s[52:53]
	v_cndmask_b32_e64 v79, 0, v78, s[40:41]
	v_cndmask_b32_e64 v180, 0, v80, s[42:43]
	v_pk_add_f32 v[166:167], v[166:167], v[170:171]
	v_pk_add_f32 v[168:169], v[172:173], v[168:169]
	v_add_f32_e32 v79, v79, v180
	v_cndmask_b32_e64 v180, 0, v82, s[44:45]
	v_pk_add_f32 v[166:167], v[166:167], v[168:169]
	v_mul_f32_e32 v62, 0x3e000000, v56
	ds_read_b64_tr_b16 v[16:17], v190 offset:4096
	v_add_f32_e32 v79, v180, v79
	v_pk_add_f32 v[166:167], v[144:145], v[166:167]
	v_mul_f32_e64 v60, |v62|, s14
	v_fma_f32 v77, v192, s21, -v77
	v_add_f32_e32 v79, v166, v79
	v_exp_f32_e32 v60, v60
	v_add_f32_e32 v77, v77, v79
	v_fma_f32 v83, v193, s21, -v83
	v_fma_f32 v144, v194, s21, -v161
	v_fma_f32 v81, v195, s21, -v81
	v_add_f32_e32 v77, v179, v77
	v_add_f32_e32 v83, v83, v79
	v_add_f32_e32 v144, v144, v79
	v_add_f32_e32 v79, v81, v79
	v_mul_f32_e32 v77, 0x3fb8aa3b, v77
	v_add_f32_e32 v83, v178, v83
	v_add_f32_e32 v79, 0, v79
	v_exp_f32_e32 v77, v77
	v_mul_f32_e32 v83, 0x3fb8aa3b, v83
	v_add_f32_e32 v144, v176, v144
	v_mul_f32_e32 v79, 0x3fb8aa3b, v79
	v_add_f32_e32 v60, 1.0, v60
	s_waitcnt lgkmcnt(6)
	s_setprio 1
	v_mfma_f32_16x16x16_bf16 v[132:135], v[20:21], v[52:53], v[132:135]
	s_setprio 0
	ds_read_b64_tr_b16 v[18:19], v190 offset:4128
	ds_read_b64_tr_b16 v[20:21], v190 offset:4160
	ds_read_b64_tr_b16 v[174:175], v190 offset:4192
	v_exp_f32_e32 v83, v83
	v_mul_f32_e32 v144, 0x3fb8aa3b, v144
	v_exp_f32_e32 v79, v79
	v_cmp_gt_f32_e64 s[52:53], s13, v60
	v_exp_f32_e32 v144, v144
	s_waitcnt lgkmcnt(3)
	s_setprio 1
	v_mfma_f32_16x16x16_bf16 v[116:119], v[16:17], v[146:147], v[116:119]
	s_setprio 0
	v_cndmask_b32_e64 v81, 0, 32, s[52:53]
	v_ldexp_f32 v60, v60, v81
	v_mad_i64_i32 v[16:17], s[0:1], s31, v246, v[162:163]
	v_mad_i64_i32 v[24:25], s[0:1], s31, v246, v[164:165]
	v_cndmask_b32_e32 v77, 0, v77, vcc
	v_log_f32_e32 v81, v60
	s_setprio 1
	v_mfma_f32_16x16x16_bf16 v[128:131], v[22:23], v[52:53], v[128:131]
	s_setprio 0
	v_cndmask_b32_e64 v61, 0, v83, s[46:47]
	v_cndmask_b32_e64 v79, 0, v79, s[50:51]
	v_cndmask_b32_e64 v63, 0, v144, s[48:49]
	s_setprio 1
	v_mfma_f32_16x16x16_bf16 v[124:127], v[28:29], v[52:53], v[124:127]
	s_setprio 0
	v_cmp_lt_f32_e64 s[54:55], |v81|, s23
	v_mul_f32_e32 v83, 0x3e000000, v58
	v_mul_f32_e64 v144, |v83|, s14
	s_setprio 1
	v_mfma_f32_16x16x16_bf16 v[120:123], v[30:31], v[52:53], v[120:123]
	s_setprio 0
	v_exp_f32_e32 v144, v144
	v_mul_f32_e32 v145, 0x3e000000, v59
	v_mul_f32_e64 v161, |v145|, s14
	s_waitcnt lgkmcnt(2)
	s_setprio 1
	v_mfma_f32_16x16x16_bf16 v[112:115], v[18:19], v[146:147], v[112:115]
	s_setprio 0
	v_exp_f32_e32 v161, v161
	v_max_f32_e32 v62, 0, v62
	s_max_i32 s0, s30, 4
	s_waitcnt lgkmcnt(1)
	s_setprio 1
	v_mfma_f32_16x16x16_bf16 v[108:111], v[20:21], v[146:147], v[108:111]
	s_setprio 0
	global_load_dwordx4 v[72:75], v[16:17], off
	global_load_dwordx4 v[68:71], v[16:17], off offset:64
	global_load_dwordx4 v[20:23], v[24:25], off offset:16
	global_load_dwordx4 v[28:31], v[24:25], off
	global_load_dwordx4 v[52:55], v[16:17], off offset:128
	global_load_dwordx4 v[48:51], v[16:17], off offset:192
	s_nop 0
	global_load_dwordx4 v[16:19], v[24:25], off offset:144
	s_nop 0
	global_load_dwordx4 v[24:27], v[24:25], off offset:128
	v_cvt_pk_bf16_f32 v60, v77, v61
	v_mul_f32_e32 v77, 0x3e000000, v57
	v_cvt_pk_bf16_f32 v61, v63, v79
	v_mul_f32_e64 v79, |v77|, s14
	v_exp_f32_e32 v79, v79
	v_mul_f32_e32 v63, 0x3f317217, v81
	v_fma_f32 v63, v81, s22, -v63
	v_fmac_f32_e32 v63, 0x3377d1cf, v81
	v_fmac_f32_e32 v63, 0x3f317217, v81
	v_add_f32_e32 v79, 1.0, v79
	v_cndmask_b32_e64 v63, v81, v63, s[54:55]
	v_cndmask_b32_e64 v81, 0, v247, s[52:53]
	v_cmp_gt_f32_e64 s[52:53], s13, v79
	v_sub_f32_e32 v63, v63, v81
	v_max_f32_e32 v77, 0, v77
	v_cndmask_b32_e64 v81, 0, 32, s[52:53]
	v_ldexp_f32 v79, v79, v81
	v_log_f32_e32 v79, v79
	v_add_f32_e32 v62, v62, v63
	v_cndmask_b32_e64 v63, 0, -v62, vcc
	v_fma_f32 v56, v56, s21, -v62
	v_mul_f32_e32 v81, 0x3f317217, v79
	v_fma_f32 v81, v79, s22, -v81
	v_fmac_f32_e32 v81, 0x3377d1cf, v79
	v_fmac_f32_e32 v81, 0x3f317217, v79
	v_cmp_lt_f32_e64 s[54:55], |v79|, s23
	s_lshl_b32 s0, s0, 4
	s_sub_i32 s31, s0, 64
	v_cndmask_b32_e64 v79, v79, v81, s[54:55]
	v_cndmask_b32_e64 v81, 0, v247, s[52:53]
	v_sub_f32_e32 v79, v79, v81
	v_add_f32_e32 v81, 1.0, v144
	v_cmp_gt_f32_e64 s[52:53], s13, v81
	v_mad_u64_u32 v[172:173], s[0:1], s31, v246, v[164:165]
	s_nop 0
	v_cndmask_b32_e64 v144, 0, 32, s[52:53]
	v_ldexp_f32 v81, v81, v144
	v_log_f32_e32 v81, v81
	v_add_f32_e32 v144, v77, v79
	v_max_f32_e32 v79, 0, v83
	v_cndmask_b32_e64 v77, 0, -v144, s[46:47]
	v_mul_f32_e32 v83, 0x3f317217, v81
	v_fma_f32 v83, v81, s22, -v83
	v_fmac_f32_e32 v83, 0x3377d1cf, v81
	v_fmac_f32_e32 v83, 0x3f317217, v81
	v_cmp_lt_f32_e64 s[54:55], |v81|, s23
	v_fma_f32 v57, v57, s21, -v144
	s_waitcnt vmcnt(11)
	s_setprio 1
	v_mfma_f32_16x16x32_bf16 v[104:107], v[104:107], v[4:7], 0
	s_setprio 0
	v_cndmask_b32_e64 v81, v81, v83, s[54:55]
	v_cndmask_b32_e64 v83, 0, v247, s[52:53]
	v_sub_f32_e32 v81, v81, v83
	v_add_f32_e32 v83, 1.0, v161
	v_cmp_gt_f32_e64 s[52:53], s13, v83
	s_waitcnt vmcnt(10)
	s_setprio 1
	v_mfma_f32_16x16x32_bf16 v[100:103], v[100:103], v[12:15], v[104:107]
	s_setprio 0
	v_cndmask_b32_e64 v161, 0, 32, s[52:53]
	v_ldexp_f32 v83, v83, v161
	v_log_f32_e32 v83, v83
	v_add_f32_e32 v161, v79, v81
	v_max_f32_e32 v81, 0, v145
	v_cndmask_b32_e64 v79, 0, -v161, s[48:49]
	v_mul_f32_e32 v145, 0x3f317217, v83
	v_fma_f32 v145, v83, s22, -v145
	v_fmac_f32_e32 v145, 0x3377d1cf, v83
	v_fmac_f32_e32 v145, 0x3f317217, v83
	v_cmp_lt_f32_e64 s[54:55], |v83|, s23
	v_fma_f32 v58, v58, s21, -v161
	v_add_u32_e32 v161, 16, v155
	v_cndmask_b32_e64 v83, v83, v145, s[54:55]
	v_cndmask_b32_e64 v145, 0, v247, s[52:53]
	v_sub_f32_e32 v83, v83, v145
	v_add_f32_e32 v145, v81, v83
	v_cndmask_b32_e64 v168, 0, -v145, s[50:51]
	v_add_f32_e32 v169, v168, v79
	v_add_f32_e32 v170, v77, v169
	v_add_f32_e32 v77, v63, v170
	ds_swizzle_b32 v79, v77 offset:swizzle(SWAP,16)
	v_mov_b32_e32 v63, v77
	v_mov_b32_e32 v81, v77
	s_nop 1
	v_permlane32_swap_b32_e32 v63, v81
	v_cmp_eq_u32_e64 s[52:53], v63, v77
	s_waitcnt lgkmcnt(0)
	v_mov_b32_e32 v83, v79
	v_fma_f32 v59, v59, s21, -v145
	v_cndmask_b32_e64 v81, v63, v81, s[52:53]
	v_mov_b32_e32 v63, v79
	s_nop 1
	v_permlane32_swap_b32_e32 v63, v83
	v_cmp_eq_u32_e64 s[52:53], v63, v79
	v_cndmask_b32_e64 v171, 0, v81, s[42:43]
	s_setprio 1
	v_mfma_f32_16x16x16_bf16 v[144:147], v[174:175], v[146:147], v[64:67]
	s_setprio 0
	v_cndmask_b32_e64 v83, v63, v83, s[52:53]
	v_cndmask_b32_e64 v63, 0, v79, s[40:41]
	v_add_f32_e32 v63, v63, v171
	v_cndmask_b32_e64 v171, 0, v83, s[44:45]
	v_add_f32_e32 v63, v171, v63
	v_add_f32_e32 v63, v167, v63
	v_add_f32_e32 v56, v56, v63
	v_add_f32_e32 v57, v57, v63
	v_add_f32_e32 v58, v58, v63
	v_add_f32_e32 v59, v59, v63
	v_add_f32_e32 v56, v170, v56
	v_add_f32_e32 v57, v169, v57
	v_add_f32_e32 v58, v168, v58
	v_add_f32_e32 v59, 0, v59
	v_mul_f32_e32 v56, 0x3fb8aa3b, v56
	v_mul_f32_e32 v57, 0x3fb8aa3b, v57
	v_mul_f32_e32 v58, 0x3fb8aa3b, v58
	v_mul_f32_e32 v59, 0x3fb8aa3b, v59
	v_exp_f32_e32 v56, v56
	v_exp_f32_e32 v57, v57
	v_exp_f32_e32 v58, v58
	v_exp_f32_e32 v59, v59
	v_cndmask_b32_e32 v56, 0, v56, vcc
	v_cndmask_b32_e64 v57, 0, v57, s[46:47]
	v_cndmask_b32_e64 v58, 0, v58, s[48:49]
	v_cndmask_b32_e64 v59, 0, v59, s[50:51]
	v_cvt_pk_bf16_f32 v168, v56, v57
	v_cvt_pk_bf16_f32 v169, v58, v59
	ds_write_b128 v153, v[40:43]
	ds_write_b128 v153, v[32:35] offset:16
	ds_read_b64_tr_b16 v[32:33], v190
	ds_read_b64_tr_b16 v[34:35], v190 offset:32
	ds_read_b64_tr_b16 v[40:41], v190 offset:64
	ds_read_b64_tr_b16 v[42:43], v190 offset:96
	ds_write_b128 v153, v[44:47] offset:4096
	ds_write_b128 v153, v[36:39] offset:4112
	s_waitcnt lgkmcnt(5)
	s_setprio 1
	v_mfma_f32_16x16x16_bf16 v[132:135], v[32:33], v[60:61], v[132:135]
	s_setprio 0
	ds_read_b64_tr_b16 v[32:33], v190 offset:4096
	v_add_u32_e32 v38, 17, v155
	v_cmp_lt_i32_e64 s[50:51], -1, v161
	s_waitcnt lgkmcnt(5)
	s_setprio 1
	v_mfma_f32_16x16x16_bf16 v[128:131], v[34:35], v[60:61], v[128:131]
	s_setprio 0
	ds_read_b64_tr_b16 v[34:35], v190 offset:4128
	ds_read_b64_tr_b16 v[36:37], v190 offset:4160
	ds_read_b64_tr_b16 v[170:171], v190 offset:4192
	v_cmp_lt_i32_e64 s[46:47], v38, v191
	s_waitcnt lgkmcnt(3)
	s_setprio 1
	v_mfma_f32_16x16x16_bf16 v[64:67], v[32:33], v[168:169], v[116:119]
	s_setprio 0
	v_add_u32_e32 v32, 18, v155
	v_cmp_lt_i32_e64 s[48:49], v32, v191
	v_add_u32_e32 v32, 19, v155
	s_waitcnt lgkmcnt(2)
	s_setprio 1
	v_mfma_f32_16x16x16_bf16 v[112:115], v[34:35], v[168:169], v[112:115]
	s_setprio 0
	v_cmp_lt_i32_e64 s[52:53], v32, v191
	v_pk_add_f32 v[32:33], v[76:77], v[78:79]
	v_pk_add_f32 v[34:35], v[82:83], v[80:81]
	s_waitcnt lgkmcnt(1)
	s_setprio 1
	v_mfma_f32_16x16x16_bf16 v[108:111], v[36:37], v[168:169], v[108:111]
	s_setprio 0
	v_add_f32_e64 v32, v32, v34
	v_add_f32_e64 v33, v33, v35
	s_and_b64 s[46:47], s[50:51], s[46:47]
	v_pk_add_f32 v[166:167], v[166:167], v[32:33]
	s_setprio 1
	v_mfma_f32_16x16x32_bf16 v[32:35], v[140:143], v[8:11], 0
	s_setprio 0
	s_and_b64 s[48:49], s[50:51], s[48:49]
	s_and_b64 s[50:51], s[50:51], s[52:53]
	v_mad_u64_u32 v[56:57], s[0:1], s31, v246, v[162:163]
	s_setprio 1
	v_mfma_f32_16x16x32_bf16 v[116:119], v[136:139], v[0:3], v[32:35]
	s_setprio 0
	global_load_dwordx4 v[80:83], v[56:57], off
	global_load_dwordx4 v[76:79], v[56:57], off offset:64
	v_mul_f32_e32 v106, 0x3e000000, v100
	s_setprio 1
	v_mfma_f32_16x16x16_bf16 v[124:127], v[40:41], v[60:61], v[124:127]
	s_setprio 0
	s_nop 3
	v_mul_f32_e32 v136, 0x3e000000, v116
	v_mul_f32_e64 v32, |v136|, s14
	v_exp_f32_e32 v36, v32
	v_max_f32_e32 v136, 0, v136
	s_setprio 1
	v_mfma_f32_16x16x16_bf16 v[120:123], v[42:43], v[60:61], v[120:123]
	s_setprio 0
	global_load_dwordx4 v[32:35], v[172:173], off offset:16
	global_load_dwordx4 v[40:43], v[172:173], off
	global_load_dwordx4 v[60:63], v[56:57], off offset:128
	s_nop 0
	global_load_dwordx4 v[56:59], v[56:57], off offset:192
	v_add_f32_e32 v36, 1.0, v36
	v_cmp_gt_f32_e32 vcc, s13, v36
	v_mul_f32_e64 v104, |v106|, s14
	v_exp_f32_e32 v104, v104
	v_cndmask_b32_e64 v37, 0, 32, vcc
	v_ldexp_f32 v36, v36, v37
	v_log_f32_e32 v137, v36
	v_cndmask_b32_e32 v140, 0, v247, vcc
	v_cmp_lt_u32_e32 vcc, v161, v191
	global_load_dwordx4 v[36:39], v[172:173], off offset:144
	global_load_dwordx4 v[44:47], v[172:173], off offset:128
	v_mul_f32_e32 v138, 0x3f317217, v137
	v_fma_f32 v138, v137, s22, -v138
	v_fmac_f32_e32 v138, 0x3377d1cf, v137
	v_fmac_f32_e32 v138, 0x3f317217, v137
	v_cmp_lt_f32_e64 s[54:55], |v137|, s23
	v_add_f32_e32 v104, 1.0, v104
	v_max_f32_e32 v106, 0, v106
	v_cndmask_b32_e64 v137, v137, v138, s[54:55]
	v_mul_f32_e32 v138, 0x3e000000, v117
	v_mul_f32_e64 v139, |v138|, s14
	v_exp_f32_e32 v139, v139
	v_sub_f32_e32 v137, v137, v140
	v_add_f32_e32 v137, v136, v137
	v_max_f32_e32 v138, 0, v138
	v_add_f32_e32 v136, 1.0, v139
	v_cmp_gt_f32_e64 s[54:55], s13, v136
	v_fma_f32 v116, v116, s21, -v137
	s_mov_b64 s[0:1], -1
	v_cndmask_b32_e64 v139, 0, 32, s[54:55]
	v_ldexp_f32 v136, v136, v139
	v_log_f32_e32 v136, v136
	v_cndmask_b32_e64 v142, 0, v247, s[54:55]
	v_cndmask_b32_e64 v139, 0, -v137, vcc
	v_mul_f32_e32 v140, 0x3f317217, v136
	v_fma_f32 v140, v136, s22, -v140
	v_fmac_f32_e32 v140, 0x3377d1cf, v136
	v_fmac_f32_e32 v140, 0x3f317217, v136
	v_cmp_lt_f32_e64 s[56:57], |v136|, s23
	s_nop 1
	v_cndmask_b32_e64 v136, v136, v140, s[56:57]
	v_mul_f32_e32 v140, 0x3e000000, v118
	v_mul_f32_e64 v141, |v140|, s14
	v_exp_f32_e32 v141, v141
	v_sub_f32_e32 v136, v136, v142
	v_add_f32_e32 v143, v138, v136
	v_max_f32_e32 v140, 0, v140
	v_add_f32_e32 v136, 1.0, v141
	v_cmp_gt_f32_e64 s[54:55], s13, v136
	v_fma_f32 v117, v117, s21, -v143
	s_nop 0
	v_cndmask_b32_e64 v138, 0, 32, s[54:55]
	v_ldexp_f32 v136, v136, v138
	v_log_f32_e32 v136, v136
	v_cndmask_b32_e64 v155, 0, v247, s[54:55]
	v_cndmask_b32_e64 v138, 0, -v143, s[46:47]
	v_mul_f32_e32 v141, 0x3f317217, v136
	v_fma_f32 v141, v136, s22, -v141
	v_fmac_f32_e32 v141, 0x3377d1cf, v136
	v_fmac_f32_e32 v141, 0x3f317217, v136
	v_cmp_lt_f32_e64 s[56:57], |v136|, s23
	s_nop 1
	v_cndmask_b32_e64 v136, v136, v141, s[56:57]
	v_mul_f32_e32 v141, 0x3e000000, v119
	v_mul_f32_e64 v142, |v141|, s14
	v_exp_f32_e32 v142, v142
	v_sub_f32_e32 v136, v136, v155
	v_add_f32_e32 v155, v140, v136
	v_max_f32_e32 v141, 0, v141
	v_add_f32_e32 v136, 1.0, v142
	v_cmp_gt_f32_e64 s[54:55], s13, v136
	v_fma_f32 v118, v118, s21, -v155
	s_nop 0
	v_cndmask_b32_e64 v140, 0, 32, s[54:55]
	v_ldexp_f32 v136, v136, v140
	v_log_f32_e32 v136, v136
	v_cndmask_b32_e64 v140, 0, -v155, s[48:49]
	v_mul_f32_e32 v142, 0x3f317217, v136
	v_fma_f32 v142, v136, s22, -v142
	v_fmac_f32_e32 v142, 0x3377d1cf, v136
	v_fmac_f32_e32 v142, 0x3f317217, v136
	v_cmp_lt_f32_e64 s[56:57], |v136|, s23
	s_nop 1
	v_cndmask_b32_e64 v136, v136, v142, s[56:57]
	v_cndmask_b32_e64 v142, 0, v247, s[54:55]
	v_sub_f32_e32 v136, v136, v142
	v_add_f32_e32 v141, v141, v136
	v_cndmask_b32_e64 v161, 0, -v141, s[50:51]
	v_add_f32_e32 v172, v161, v140
	v_add_f32_e32 v173, v138, v172
	v_add_f32_e32 v136, v139, v173
	ds_swizzle_b32 v140, v136 offset:swizzle(SWAP,16)
	v_mov_b32_e32 v138, v136
	v_mov_b32_e32 v139, v136
	s_nop 1
	v_permlane32_swap_b32_e32 v138, v139
	v_cmp_eq_u32_e64 s[52:53], v138, v136
	s_waitcnt lgkmcnt(0)
	v_mov_b32_e32 v142, v140
	v_fma_f32 v119, v119, s21, -v141
	v_cndmask_b32_e64 v138, v138, v139, s[52:53]
	v_mov_b32_e32 v139, v140
	s_nop 1
	v_permlane32_swap_b32_e32 v139, v142
	v_cmp_eq_u32_e64 s[52:53], v139, v140
	v_cndmask_b32_e64 v174, 0, v138, s[42:43]
	s_nop 0
	v_cndmask_b32_e64 v142, v139, v142, s[52:53]
	v_cndmask_b32_e64 v139, 0, v140, s[40:41]
	v_add_f32_e32 v139, v139, v174
	v_cndmask_b32_e64 v174, 0, v142, s[44:45]
	v_add_f32_e32 v139, v174, v139
	v_add_f32_e32 v139, v166, v139
	v_add_f32_e32 v118, v118, v139
	v_add_f32_e32 v118, v161, v118
	v_add_f32_e32 v116, v116, v139
	v_mul_f32_e32 v118, 0x3fb8aa3b, v118
	v_add_f32_e32 v116, v173, v116
	v_add_f32_e32 v117, v117, v139
	v_exp_f32_e32 v118, v118
	v_add_f32_e32 v119, v119, v139
	v_mul_f32_e32 v116, 0x3fb8aa3b, v116
	v_add_f32_e32 v117, v172, v117
	v_add_f32_e32 v119, 0, v119
	v_exp_f32_e32 v116, v116
	v_mul_f32_e32 v117, 0x3fb8aa3b, v117
	v_mul_f32_e32 v119, 0x3fb8aa3b, v119
	v_exp_f32_e32 v117, v117
	v_exp_f32_e32 v119, v119
	v_cmp_gt_f32_e64 s[52:53], s13, v104
	v_cndmask_b32_e64 v107, 0, v118, s[48:49]
	v_cndmask_b32_e32 v116, 0, v116, vcc
	v_cndmask_b32_e64 v118, 0, 32, s[52:53]
	v_ldexp_f32 v104, v104, v118
	v_log_f32_e32 v118, v104
	v_cndmask_b32_e64 v105, 0, v117, s[46:47]
	v_cndmask_b32_e64 v117, 0, v119, s[50:51]
	v_cvt_pk_bf16_f32 v104, v116, v105
	v_mul_f32_e32 v116, 0x3e000000, v101
	v_cvt_pk_bf16_f32 v105, v107, v117
	v_mul_f32_e64 v117, |v116|, s14
	v_exp_f32_e32 v117, v117
	v_mul_f32_e32 v107, 0x3f317217, v118
	v_fma_f32 v107, v118, s22, -v107
	v_fmac_f32_e32 v107, 0x3377d1cf, v118
	v_fmac_f32_e32 v107, 0x3f317217, v118
	v_cmp_lt_f32_e64 s[54:55], |v118|, s23
	v_add_f32_e32 v117, 1.0, v117
	v_mul_f32_e32 v119, 0x3e000000, v102
	v_cndmask_b32_e64 v107, v118, v107, s[54:55]
	v_cndmask_b32_e64 v118, 0, v247, s[52:53]
	v_cmp_gt_f32_e64 s[52:53], s13, v117
	v_sub_f32_e32 v107, v107, v118
	v_mul_f32_e64 v137, |v119|, s14
	v_cndmask_b32_e64 v118, 0, 32, s[52:53]
	v_ldexp_f32 v117, v117, v118
	v_log_f32_e32 v117, v117
	v_exp_f32_e32 v137, v137
	v_mul_f32_e32 v139, 0x3e000000, v103
	v_mul_f32_e64 v141, |v139|, s14
	v_mul_f32_e32 v118, 0x3f317217, v117
	v_fma_f32 v118, v117, s22, -v118
	v_fmac_f32_e32 v118, 0x3377d1cf, v117
	v_fmac_f32_e32 v118, 0x3f317217, v117
	v_cmp_lt_f32_e64 s[54:55], |v117|, s23
	v_exp_f32_e32 v141, v141
	v_max_f32_e32 v119, 0, v119
	v_cndmask_b32_e64 v117, v117, v118, s[54:55]
	v_cndmask_b32_e64 v118, 0, v247, s[52:53]
	v_sub_f32_e32 v117, v117, v118
	v_add_f32_e32 v118, 1.0, v137
	v_cmp_gt_f32_e64 s[52:53], s13, v118
	v_max_f32_e32 v139, 0, v139
	v_max_f32_e32 v116, 0, v116
	v_cndmask_b32_e64 v137, 0, 32, s[52:53]
	v_ldexp_f32 v118, v118, v137
	v_log_f32_e32 v118, v118
	v_add_f32_e32 v116, v116, v117
	v_add_f32_e32 v106, v106, v107
	v_cndmask_b32_e64 v117, 0, -v116, s[46:47]
	v_mul_f32_e32 v137, 0x3f317217, v118
	v_fma_f32 v137, v118, s22, -v137
	v_fmac_f32_e32 v137, 0x3377d1cf, v118
	v_fmac_f32_e32 v137, 0x3f317217, v118
	v_cmp_lt_f32_e64 s[54:55], |v118|, s23
	v_cndmask_b32_e64 v107, 0, -v106, vcc
	v_fma_f32 v100, v100, s21, -v106
	v_cndmask_b32_e64 v118, v118, v137, s[54:55]
	v_cndmask_b32_e64 v137, 0, v247, s[52:53]
	v_sub_f32_e32 v118, v118, v137
	v_add_f32_e32 v137, 1.0, v141
	v_cmp_gt_f32_e64 s[52:53], s13, v137
	v_add_f32_e32 v118, v119, v118
	v_cndmask_b32_e64 v119, 0, -v118, s[48:49]
	v_cndmask_b32_e64 v141, 0, 32, s[52:53]
	v_ldexp_f32 v137, v137, v141
	v_log_f32_e32 v137, v137
	v_fma_f32 v101, v101, s21, -v116
	v_fma_f32 v102, v102, s21, -v118
	v_mul_f32_e32 v141, 0x3f317217, v137
	v_fma_f32 v141, v137, s22, -v141
	v_fmac_f32_e32 v141, 0x3377d1cf, v137
	v_fmac_f32_e32 v141, 0x3f317217, v137
	v_cmp_lt_f32_e64 s[54:55], |v137|, s23
	s_nop 1
	v_cndmask_b32_e64 v137, v137, v141, s[54:55]
	v_cndmask_b32_e64 v141, 0, v247, s[52:53]
	v_sub_f32_e32 v137, v137, v141
	v_add_f32_e32 v155, v139, v137
	v_cndmask_b32_e64 v161, 0, -v155, s[50:51]
	v_add_f32_e32 v119, v161, v119
	v_add_f32_e32 v117, v117, v119
	v_add_f32_e32 v137, v107, v117
	ds_swizzle_b32 v141, v137 offset:swizzle(SWAP,16)
	v_mov_b32_e32 v107, v137
	v_mov_b32_e32 v139, v137
	s_nop 1
	v_permlane32_swap_b32_e32 v107, v139
	v_cmp_eq_u32_e64 s[52:53], v107, v137
	s_waitcnt lgkmcnt(0)
	v_mov_b32_e32 v143, v141
	v_fma_f32 v103, v103, s21, -v155
	v_cndmask_b32_e64 v139, v107, v139, s[52:53]
	v_mov_b32_e32 v107, v141
	s_nop 1
	v_permlane32_swap_b32_e32 v107, v143
	v_cmp_eq_u32_e64 s[52:53], v107, v141
	v_cndmask_b32_e64 v172, 0, v139, s[42:43]
	s_nop 0
	v_cndmask_b32_e64 v143, v107, v143, s[52:53]
	v_cndmask_b32_e64 v107, 0, v141, s[40:41]
	v_add_f32_e32 v107, v107, v172
	v_cndmask_b32_e64 v172, 0, v143, s[44:45]
	v_add_f32_e32 v107, v172, v107
	v_add_f32_e32 v107, v167, v107
	v_add_f32_e32 v100, v100, v107
	v_add_f32_e32 v101, v101, v107
	v_add_f32_e32 v100, v117, v100
	v_add_f32_e32 v101, v119, v101
	v_add_f32_e32 v102, v102, v107
	v_add_f32_e32 v103, v103, v107
	v_mul_f32_e32 v100, 0x3fb8aa3b, v100
	v_mul_f32_e32 v101, 0x3fb8aa3b, v101
	v_add_f32_e32 v102, v161, v102
	v_add_f32_e32 v103, 0, v103
	v_exp_f32_e32 v100, v100
	v_exp_f32_e32 v101, v101
	v_mul_f32_e32 v102, 0x3fb8aa3b, v102
	v_mul_f32_e32 v103, 0x3fb8aa3b, v103
	v_exp_f32_e32 v102, v102
	v_exp_f32_e32 v103, v103
	v_cndmask_b32_e32 v100, 0, v100, vcc
	v_cndmask_b32_e64 v101, 0, v101, s[46:47]
	v_cndmask_b32_e64 v102, 0, v102, s[48:49]
	v_cndmask_b32_e64 v103, 0, v103, s[50:51]
	v_cvt_pk_bf16_f32 v100, v100, v101
	v_cvt_pk_bf16_f32 v101, v102, v103
	ds_write_b128 v153, v[96:99]
	ds_write_b128 v153, v[92:95] offset:16
	ds_read_b64_tr_b16 v[96:97], v190
	ds_read_b64_tr_b16 v[98:99], v190 offset:32
	ds_read_b64_tr_b16 v[102:103], v190 offset:64
	ds_read_b64_tr_b16 v[106:107], v190 offset:96
	s_waitcnt vmcnt(16)
	ds_write_b128 v153, v[88:91] offset:4096
	ds_write_b128 v153, v[84:87] offset:4112
	ds_read_b64_tr_b16 v[84:85], v190 offset:4096
	ds_read_b64_tr_b16 v[86:87], v190 offset:4128
	ds_read_b64_tr_b16 v[88:89], v190 offset:4160
	ds_read_b64_tr_b16 v[90:91], v190 offset:4192
	s_setprio 1
	v_mfma_f32_16x16x16_bf16 v[92:95], v[170:171], v[168:169], v[144:147]
	s_setprio 0
	s_and_b64 vcc, s[4:5], exec
	s_mov_b64 s[4:5], -1
	s_waitcnt lgkmcnt(9)
	s_setprio 1
	v_mfma_f32_16x16x16_bf16 v[132:135], v[96:97], v[104:105], v[132:135]
	s_setprio 0
	s_waitcnt lgkmcnt(8)
	s_setprio 1
	v_mfma_f32_16x16x16_bf16 v[128:131], v[98:99], v[104:105], v[128:131]
	s_setprio 0
	s_waitcnt lgkmcnt(7)
	s_setprio 1
	v_mfma_f32_16x16x16_bf16 v[124:127], v[102:103], v[104:105], v[124:127]
	s_setprio 0
	s_waitcnt lgkmcnt(6)
	s_setprio 1
	v_mfma_f32_16x16x16_bf16 v[120:123], v[106:107], v[104:105], v[120:123]
	s_setprio 0
	s_waitcnt lgkmcnt(3)
	s_setprio 1
	v_mfma_f32_16x16x16_bf16 v[116:119], v[84:85], v[100:101], v[64:67]
	s_setprio 0
	s_waitcnt lgkmcnt(2)
	s_setprio 1
	v_mfma_f32_16x16x16_bf16 v[112:115], v[86:87], v[100:101], v[112:115]
	s_setprio 0
	s_waitcnt lgkmcnt(1)
	s_setprio 1
	v_mfma_f32_16x16x16_bf16 v[108:111], v[88:89], v[100:101], v[108:111]
	s_setprio 0
	s_waitcnt lgkmcnt(0)
	s_setprio 1
	v_mfma_f32_16x16x16_bf16 v[64:67], v[90:91], v[100:101], v[92:95]
	s_setprio 0
	s_cbranch_vccz .LBB0_475
	v_pk_add_f32 v[84:85], v[136:137], v[140:141]
	v_pk_add_f32 v[86:87], v[142:143], v[138:139]
	s_nop 0
	v_pk_add_f32 v[84:85], v[84:85], v[86:87]
	s_nop 0
	v_pk_add_f32 v[144:145], v[166:167], v[84:85]
	s_nop 0
	v_cmp_gt_f32_e32 vcc, s24, v144
	v_cmp_gt_f32_e64 s[46:47], s24, v145
	s_and_b64 s[0:1], vcc, s[46:47]
	v_cndmask_b32_e64 v84, 0, 1, s[0:1]
	v_cmp_ne_u32_e32 vcc, 0, v84
	s_cmp_eq_u64 vcc, exec
	s_cselect_b64 s[4:5], -1, 0
	s_sub_i32 s29, s29, 48
	s_add_i32 s30, s30, -3
	s_mov_b64 s[0:1], 0
	s_branch .LBB0_475
